# EpiProj: per-block vmcnt(0) (only needed by the unused global row-scale load) no longer drains the previous block's store; first-iteration K-loop waits widened by the epilogue store count (tiles after
# speedup vs baseline: 1.0264x; 1.0041x over previous
; #define PG8_STAGE(bufoff, gbase, voff) do { _Pragma("unroll") for (int _i = 0; _i < 2; ++_i) \
;         __builtin_amdgcn_global_load_lds((const unsigned*)((const char*)(gbase) + (voff)[_i]), (PG8_LAS unsigned*)(lds + (bufoff) + ldsw + _i * 8192), 16, 0, 0); } while (0)
; #define PG8_LDA(dst, b, h) do { _Pragma("unroll") for (int m = 0; m < 4; ++m) _Pragma("unroll") for (int k = 0; k < 2; ++k) dst[m][k] = *(const PG8_LAS bf16x8*)(lds + PG8_SA(b, h) + aoff + m * 2048 + k * 1024); } while (0)
; #define PG8_LDB(dst, b, h) do { _Pragma("unroll") for (int n = 0; n < 2; ++n) _Pragma("unroll") for (int k = 0; k < 2; ++k) dst[n][k] = *(const PG8_LAS bf16x8*)(lds + PG8_SB(b, h) + boff + n * 2048 + k * 1024); } while (0)
; #define PG8_WAIT_V(n) asm volatile("s_waitcnt vmcnt(" #n ")" ::: "memory")
; #define PG8_WAIT_L(n) asm volatile("s_waitcnt lgkmcnt(" #n ")" ::: "memory")
; #define PG8_BAR __builtin_amdgcn_s_barrier()
; #define PG8_SCHED __builtin_amdgcn_sched_barrier(0)
; template <class Epi, class Sched, bool ALIGN_EPI = false, bool SP2 = false>
; __device__ __forceinline__ void gemm_phase(PG8_LAS unsigned char* lds, const Gemm g, const Sched& S, const Epi& E) {
;     ...
;         const bool has_next = S.next(ui + 1, nxt);
;         const char* nA = has_next ? (const char*)g.A + (size_t)nxt.pm * tstep : cA; const char* nB = has_next ? (const char*)g.Bt + (size_t)nxt.pn * tstep : cB;
;         for (int t = 0; t < nt; t += 2) {
;             const bool last = (t == nt - 2);
;             const char* a1 = cA + (size_t)(t + 1) * kstep;
;             const char* a2 = last ? nA : cA + (size_t)(t + 2) * kstep; const char* b2 = last ? nB : cB + (size_t)(t + 2) * kstep;
;             const char* a3 = a2 + kstep; const char* b3 = b2 + kstep;
;             if (last && has_next) S.a_ready(nxt);
;             if constexpr (SP2) {
;             PG8_LDB(B0, 0, 0); PG8_LDB(B1, 0, 1); PG8_SCHED; PG8_LDA(At, 0, 0); PG8_STAGE(PG8_SA(1, 1), a1 + hstep, voffA);
;             PG8_WAIT_V(8); PG8_WAIT_L(0); PG8_BAR; PG8_MMA(0, 0, At, B0); PG8_MMA(0, 1, At, B1); PG8_BAR; PG8_SCHED;
;             PG8_LDA(At, 0, 1); PG8_STAGE(PG8_SB(0, 0), b2, voffB); PG8_STAGE(PG8_SB(0, 1), b2 + hstep, voffB); PG8_STAGE(PG8_SA(0, 0), a2, voffA);
;             PG8_WAIT_V(8); PG8_WAIT_L(0); PG8_BAR; PG8_MMA(1, 0, At, B0); PG8_MMA(1, 1, At, B1); PG8_BAR; PG8_SCHED;
.LBB0_109:
	s_ashr_i32 s75, s74, 31
	s_lshl_b64 s[60:61], s[74:75], 19
	s_add_u32 s76, s40, s60
	s_addc_u32 s77, s41, s61
	s_and_b64 s[60:61], s[4:5], exec
	s_cselect_b32 s1, s77, s7
	s_cselect_b32 s33, s76, s6
	s_ashr_i32 s73, s72, 31
	s_lshl_b64 s[60:61], s[72:73], 19
	s_add_u32 s78, s20, s60
	s_addc_u32 s79, s21, s61
	s_and_b64 s[60:61], s[4:5], exec
	s_cselect_b32 s60, s79, s9
	s_cselect_b32 s61, s78, s8
	s_add_u32 s6, s6, 0x40080
	s_addc_u32 s7, s7, 0
	s_add_u32 s73, s8, 0x100
	s_addc_u32 s75, s9, 0
	s_mov_b32 s84, -2
	ds_read_b128 v[146:149], v160
	ds_read_b128 v[150:153], v160 offset:1024
	ds_read_b128 v[154:157], v160 offset:2048
	ds_read_b128 v[166:169], v160 offset:3072
	ds_read_b128 v[170:173], v161
	ds_read_b128 v[174:177], v161 offset:1024
	ds_read_b128 v[178:181], v161 offset:2048
	ds_read_b128 v[182:185], v161 offset:3072
	s_add_u32 s8, s6, 0xfffc0080
	s_addc_u32 s9, s7, -1
	s_cmp_eq_u32 s84, 12
	s_cselect_b32 s83, s1, s9
	s_cselect_b32 s82, s33, s8
	s_cselect_b32 s9, s60, s75
	s_cselect_b32 s8, s61, s73
	v_lshl_add_u64 v[220:221], s[6:7], 0, v[138:139]
	s_add_i32 m0, s81, 0xc000
	ds_read_b128 v[186:189], v162
	ds_read_b128 v[190:193], v162 offset:1024
	ds_read_b128 v[194:197], v162 offset:2048
	ds_read_b128 v[198:201], v162 offset:3072
	ds_read_b128 v[202:205], v162 offset:4096
	ds_read_b128 v[208:211], v162 offset:5120
	ds_read_b128 v[212:215], v162 offset:6144
	ds_read_b128 v[216:219], v162 offset:7168
	global_load_lds_dwordx4 v[220:221], off
	v_lshl_add_u64 v[220:221], s[6:7], 0, v[140:141]
	s_add_i32 m0, s81, 0xe000
	s_nop 0
	global_load_lds_dwordx4 v[220:221], off
	s_waitcnt vmcnt(24)
	s_cmp_gt_u32 s91, 1
	s_cbranch_scc1 .Lpw_110_0
	s_waitcnt vmcnt(8)
.Lpw_110_0:
	s_waitcnt lgkmcnt(0)
	s_barrier
	s_setprio 1
	s_waitcnt lgkmcnt(0)
	v_mfma_f32_16x16x32_bf16 v[126:129], v[146:149], v[186:189], 0
	v_mfma_f32_16x16x32_bf16 v[122:125], v[154:157], v[186:189], 0
	v_mfma_f32_16x16x32_bf16 v[118:121], v[146:149], v[194:197], 0
	v_mfma_f32_16x16x32_bf16 v[114:117], v[154:157], v[194:197], 0
	v_mfma_f32_16x16x32_bf16 v[110:113], v[146:149], v[202:205], 0
	v_mfma_f32_16x16x32_bf16 v[106:109], v[154:157], v[202:205], 0
	v_mfma_f32_16x16x32_bf16 v[102:105], v[146:149], v[212:215], 0
	v_mfma_f32_16x16x32_bf16 v[98:101], v[154:157], v[212:215], 0
	v_mfma_f32_16x16x32_bf16 v[126:129], v[150:153], v[190:193], v[126:129]
	v_mfma_f32_16x16x32_bf16 v[122:125], v[166:169], v[190:193], v[122:125]
	v_mfma_f32_16x16x32_bf16 v[118:121], v[150:153], v[198:201], v[118:121]
	v_mfma_f32_16x16x32_bf16 v[114:117], v[166:169], v[198:201], v[114:117]
	v_mfma_f32_16x16x32_bf16 v[110:113], v[150:153], v[208:211], v[110:113]
	v_mfma_f32_16x16x32_bf16 v[106:109], v[166:169], v[208:211], v[106:109]
	v_mfma_f32_16x16x32_bf16 v[102:105], v[150:153], v[216:219], v[102:105]
	v_mfma_f32_16x16x32_bf16 v[98:101], v[166:169], v[216:219], v[98:101]
	s_setprio 0
	s_setprio 1
	v_mfma_f32_16x16x32_bf16 v[62:65], v[170:173], v[186:189], 0
	v_mfma_f32_16x16x32_bf16 v[58:61], v[178:181], v[186:189], 0
	v_mfma_f32_16x16x32_bf16 v[54:57], v[170:173], v[194:197], 0
	v_mfma_f32_16x16x32_bf16 v[50:53], v[178:181], v[194:197], 0
	v_mfma_f32_16x16x32_bf16 v[46:49], v[170:173], v[202:205], 0
	v_mfma_f32_16x16x32_bf16 v[42:45], v[178:181], v[202:205], 0
	v_mfma_f32_16x16x32_bf16 v[38:41], v[170:173], v[212:215], 0
	v_mfma_f32_16x16x32_bf16 v[34:37], v[178:181], v[212:215], 0
	v_mfma_f32_16x16x32_bf16 v[62:65], v[174:177], v[190:193], v[62:65]
	v_mfma_f32_16x16x32_bf16 v[58:61], v[182:185], v[190:193], v[58:61]
	v_mfma_f32_16x16x32_bf16 v[54:57], v[174:177], v[198:201], v[54:57]
	v_mfma_f32_16x16x32_bf16 v[50:53], v[182:185], v[198:201], v[50:53]
	v_mfma_f32_16x16x32_bf16 v[46:49], v[174:177], v[208:211], v[46:49]
	v_mfma_f32_16x16x32_bf16 v[42:45], v[182:185], v[208:211], v[42:45]
	v_mfma_f32_16x16x32_bf16 v[38:41], v[174:177], v[216:219], v[38:41]
	v_mfma_f32_16x16x32_bf16 v[34:37], v[182:185], v[216:219], v[34:37]
	s_setprio 0
	s_barrier
	s_add_i32 s85, s30, s87
	s_mov_b32 m0, s85
	ds_read_b128 v[186:189], v162 offset:16384
	ds_read_b128 v[190:193], v162 offset:17408
	ds_read_b128 v[194:197], v162 offset:18432
	ds_read_b128 v[198:201], v162 offset:19456
	ds_read_b128 v[202:205], v162 offset:20480
	ds_read_b128 v[208:211], v162 offset:21504
	ds_read_b128 v[212:215], v162 offset:22528
	ds_read_b128 v[216:219], v162 offset:23552
	global_load_lds_dwordx4 v132, s[8:9]
	s_add_i32 m0, s85, 0x2000
	s_add_u32 vcc_lo, s8, 0x40000
	v_lshl_add_u64 v[222:223], s[8:9], 0, v[136:137]
	s_addc_u32 vcc_hi, s9, 0
	s_add_i32 s85, s31, s87
	global_load_lds_dwordx4 v136, s[8:9]
	s_mov_b32 m0, s85
	v_lshl_add_u64 v[226:227], s[82:83], 0, v[134:135]
	global_load_lds_dwordx4 v132, vcc
	s_add_i32 m0, s85, 0x2000
	s_nop 0
	global_load_lds_dwordx4 v136, vcc
	v_lshl_add_u64 v[224:225], s[82:83], 0, v[130:131]
	s_mov_b32 m0, s81
	s_nop 0
	global_load_lds_dwordx4 v130, s[82:83]
	s_mov_b32 m0, s88
	s_nop 0
	global_load_lds_dwordx4 v134, s[82:83]
	s_waitcnt vmcnt(24)
	s_cmp_gt_u32 s91, 1
	s_cbranch_scc1 .Lpw_110_1
	s_waitcnt vmcnt(8)
; #define PG8_STAGE(bufoff, gbase, voff) do { _Pragma("unroll") for (int _i = 0; _i < 2; ++_i) \
;         __builtin_amdgcn_global_load_lds((const unsigned*)((const char*)(gbase) + (voff)[_i]), (PG8_LAS unsigned*)(lds + (bufoff) + ldsw + _i * 8192), 16, 0, 0); } while (0)
; #define PG8_LDA(dst, b, h) do { _Pragma("unroll") for (int m = 0; m < 4; ++m) _Pragma("unroll") for (int k = 0; k < 2; ++k) dst[m][k] = *(const PG8_LAS bf16x8*)(lds + PG8_SA(b, h) + aoff + m * 2048 + k * 1024); } while (0)
; #define PG8_LDB(dst, b, h) do { _Pragma("unroll") for (int n = 0; n < 2; ++n) _Pragma("unroll") for (int k = 0; k < 2; ++k) dst[n][k] = *(const PG8_LAS bf16x8*)(lds + PG8_SB(b, h) + boff + n * 2048 + k * 1024); } while (0)
; #define PG8_MMA(ai, bj, At, Bt) do { __builtin_amdgcn_s_setprio(1); _Pragma("unroll") for (int m = 0; m < 4; ++m) _Pragma("unroll") for (int n = 0; n < 2; ++n) _Pragma("unroll") for (int k = 0; k < 2; ++k) \
;         acc[ai][bj][m][n] = __builtin_amdgcn_mfma_f32_16x16x32_bf16(Bt[n][k], At[m][k], acc[ai][bj][m][n], 0, 0, 0); __builtin_amdgcn_s_setprio(0); } while (0)
; #define PG8_WAIT_V(n) asm volatile("s_waitcnt vmcnt(" #n ")" ::: "memory")
; #define PG8_WAIT_L(n) asm volatile("s_waitcnt lgkmcnt(" #n ")" ::: "memory")
; #define PG8_BAR __builtin_amdgcn_s_barrier()
; #define PG8_SCHED __builtin_amdgcn_sched_barrier(0)
; template <class Epi, class Sched, bool ALIGN_EPI = false, bool SP2 = false>
; __device__ __forceinline__ void gemm_phase(PG8_LAS unsigned char* lds, const Gemm g, const Sched& S, const Epi& E) {
;     ...
;             PG8_WAIT_V(8); PG8_WAIT_L(0); PG8_BAR; PG8_MMA(1, 0, At, B0); PG8_MMA(1, 1, At, B1); PG8_BAR; PG8_SCHED;
;             PG8_LDB(B0, 1, 0); PG8_LDB(B1, 1, 1); PG8_SCHED; PG8_LDA(At, 1, 0); PG8_STAGE(PG8_SA(0, 1), a2 + hstep, voffA);
;             PG8_WAIT_V(8); PG8_WAIT_L(0); PG8_BAR; PG8_MMA(0, 0, At, B0); PG8_MMA(0, 1, At, B1); PG8_BAR; PG8_SCHED;
.Lpw_110_1:
	s_waitcnt lgkmcnt(0)
	s_barrier
	s_setprio 1
	s_waitcnt lgkmcnt(0)
	v_mfma_f32_16x16x32_bf16 v[94:97], v[146:149], v[186:189], 0
	v_mfma_f32_16x16x32_bf16 v[90:93], v[154:157], v[186:189], 0
	v_mfma_f32_16x16x32_bf16 v[86:89], v[146:149], v[194:197], 0
	v_mfma_f32_16x16x32_bf16 v[82:85], v[154:157], v[194:197], 0
	v_mfma_f32_16x16x32_bf16 v[78:81], v[146:149], v[202:205], 0
	v_mfma_f32_16x16x32_bf16 v[74:77], v[154:157], v[202:205], 0
	v_mfma_f32_16x16x32_bf16 v[70:73], v[146:149], v[212:215], 0
	v_mfma_f32_16x16x32_bf16 v[66:69], v[154:157], v[212:215], 0
	v_mfma_f32_16x16x32_bf16 v[94:97], v[150:153], v[190:193], v[94:97]
	v_mfma_f32_16x16x32_bf16 v[90:93], v[166:169], v[190:193], v[90:93]
	v_mfma_f32_16x16x32_bf16 v[86:89], v[150:153], v[198:201], v[86:89]
	v_mfma_f32_16x16x32_bf16 v[82:85], v[166:169], v[198:201], v[82:85]
	v_mfma_f32_16x16x32_bf16 v[78:81], v[150:153], v[208:211], v[78:81]
	v_mfma_f32_16x16x32_bf16 v[74:77], v[166:169], v[208:211], v[74:77]
	v_mfma_f32_16x16x32_bf16 v[70:73], v[150:153], v[216:219], v[70:73]
	v_mfma_f32_16x16x32_bf16 v[66:69], v[166:169], v[216:219], v[66:69]
	s_setprio 0
	s_setprio 1
	v_mfma_f32_16x16x32_bf16 v[30:33], v[170:173], v[186:189], 0
	v_mfma_f32_16x16x32_bf16 v[26:29], v[178:181], v[186:189], 0
	v_mfma_f32_16x16x32_bf16 v[22:25], v[170:173], v[194:197], 0
	v_mfma_f32_16x16x32_bf16 v[18:21], v[178:181], v[194:197], 0
	v_mfma_f32_16x16x32_bf16 v[14:17], v[170:173], v[202:205], 0
	v_mfma_f32_16x16x32_bf16 v[10:13], v[178:181], v[202:205], 0
	v_mfma_f32_16x16x32_bf16 v[6:9], v[170:173], v[212:215], 0
	v_mfma_f32_16x16x32_bf16 v[2:5], v[178:181], v[212:215], 0
	v_mfma_f32_16x16x32_bf16 v[30:33], v[174:177], v[190:193], v[30:33]
	v_mfma_f32_16x16x32_bf16 v[26:29], v[182:185], v[190:193], v[26:29]
	v_mfma_f32_16x16x32_bf16 v[22:25], v[174:177], v[198:201], v[22:25]
	v_mfma_f32_16x16x32_bf16 v[18:21], v[182:185], v[198:201], v[18:21]
	v_mfma_f32_16x16x32_bf16 v[14:17], v[174:177], v[208:211], v[14:17]
	v_mfma_f32_16x16x32_bf16 v[10:13], v[182:185], v[208:211], v[10:13]
	v_mfma_f32_16x16x32_bf16 v[6:9], v[174:177], v[216:219], v[6:9]
	v_mfma_f32_16x16x32_bf16 v[2:5], v[182:185], v[216:219], v[2:5]
	s_setprio 0
	s_barrier
	s_add_i32 s85, 0, 0x18000
	v_add_u32_e32 v165, s85, v158
	s_add_i32 vcc_lo, 0, 0x1c000
	ds_read_b128 v[146:149], v165
	ds_read_b128 v[150:153], v165 offset:1024
	ds_read_b128 v[154:157], v165 offset:2048
	ds_read_b128 v[166:169], v165 offset:3072
	v_add_u32_e32 v165, vcc_lo, v158
	ds_read_b128 v[170:173], v165
	ds_read_b128 v[174:177], v165 offset:1024
	ds_read_b128 v[178:181], v165 offset:2048
	ds_read_b128 v[182:185], v165 offset:3072
	s_add_u32 s82, s82, 0x40000
	s_addc_u32 s83, s83, 0
	s_mov_b32 m0, s89
	ds_read_b128 v[186:189], v162 offset:32768
	ds_read_b128 v[190:193], v162 offset:33792
	ds_read_b128 v[194:197], v162 offset:34816
	ds_read_b128 v[198:201], v162 offset:35840
	ds_read_b128 v[202:205], v162 offset:36864
	ds_read_b128 v[208:211], v162 offset:37888
	ds_read_b128 v[212:215], v162 offset:38912
	ds_read_b128 v[216:219], v162 offset:39936
	global_load_lds_dwordx4 v130, s[82:83]
	s_mov_b32 m0, s90
	s_nop 0
	global_load_lds_dwordx4 v134, s[82:83]
	s_waitcnt vmcnt(8)
	s_waitcnt lgkmcnt(0)
	s_barrier
	s_setprio 1
	s_waitcnt lgkmcnt(0)
	v_mfma_f32_16x16x32_bf16 v[126:129], v[146:149], v[186:189], v[126:129]
	v_mfma_f32_16x16x32_bf16 v[122:125], v[154:157], v[186:189], v[122:125]
	v_mfma_f32_16x16x32_bf16 v[118:121], v[146:149], v[194:197], v[118:121]
	v_mfma_f32_16x16x32_bf16 v[114:117], v[154:157], v[194:197], v[114:117]
	v_mfma_f32_16x16x32_bf16 v[110:113], v[146:149], v[202:205], v[110:113]
	v_mfma_f32_16x16x32_bf16 v[106:109], v[154:157], v[202:205], v[106:109]
	v_mfma_f32_16x16x32_bf16 v[102:105], v[146:149], v[212:215], v[102:105]
	v_mfma_f32_16x16x32_bf16 v[98:101], v[154:157], v[212:215], v[98:101]
	v_mfma_f32_16x16x32_bf16 v[126:129], v[150:153], v[190:193], v[126:129]
	v_mfma_f32_16x16x32_bf16 v[122:125], v[166:169], v[190:193], v[122:125]
	v_mfma_f32_16x16x32_bf16 v[118:121], v[150:153], v[198:201], v[118:121]
	v_mfma_f32_16x16x32_bf16 v[114:117], v[166:169], v[198:201], v[114:117]
	v_mfma_f32_16x16x32_bf16 v[110:113], v[150:153], v[208:211], v[110:113]
	v_mfma_f32_16x16x32_bf16 v[106:109], v[166:169], v[208:211], v[106:109]
	v_mfma_f32_16x16x32_bf16 v[102:105], v[150:153], v[216:219], v[102:105]
	v_mfma_f32_16x16x32_bf16 v[98:101], v[166:169], v[216:219], v[98:101]
	s_setprio 0
	s_setprio 1
	v_mfma_f32_16x16x32_bf16 v[62:65], v[170:173], v[186:189], v[62:65]
	v_mfma_f32_16x16x32_bf16 v[58:61], v[178:181], v[186:189], v[58:61]
	v_mfma_f32_16x16x32_bf16 v[54:57], v[170:173], v[194:197], v[54:57]
	v_mfma_f32_16x16x32_bf16 v[50:53], v[178:181], v[194:197], v[50:53]
	v_mfma_f32_16x16x32_bf16 v[46:49], v[170:173], v[202:205], v[46:49]
	v_mfma_f32_16x16x32_bf16 v[42:45], v[178:181], v[202:205], v[42:45]
	v_mfma_f32_16x16x32_bf16 v[38:41], v[170:173], v[212:215], v[38:41]
	v_mfma_f32_16x16x32_bf16 v[34:37], v[178:181], v[212:215], v[34:37]
	v_mfma_f32_16x16x32_bf16 v[62:65], v[174:177], v[190:193], v[62:65]
	v_mfma_f32_16x16x32_bf16 v[58:61], v[182:185], v[190:193], v[58:61]
	v_mfma_f32_16x16x32_bf16 v[54:57], v[174:177], v[198:201], v[54:57]
	v_mfma_f32_16x16x32_bf16 v[50:53], v[182:185], v[198:201], v[50:53]
	v_mfma_f32_16x16x32_bf16 v[46:49], v[174:177], v[208:211], v[46:49]
	v_mfma_f32_16x16x32_bf16 v[42:45], v[182:185], v[208:211], v[42:45]
	v_mfma_f32_16x16x32_bf16 v[38:41], v[174:177], v[216:219], v[38:41]
	v_mfma_f32_16x16x32_bf16 v[34:37], v[182:185], v[216:219], v[34:37]
	s_setprio 0
	s_barrier
; #define PG8_STAGE(bufoff, gbase, voff) do { _Pragma("unroll") for (int _i = 0; _i < 2; ++_i) \
;         __builtin_amdgcn_global_load_lds((const unsigned*)((const char*)(gbase) + (voff)[_i]), (PG8_LAS unsigned*)(lds + (bufoff) + ldsw + _i * 8192), 16, 0, 0); } while (0)
; #define PG8_LDA(dst, b, h) do { _Pragma("unroll") for (int m = 0; m < 4; ++m) _Pragma("unroll") for (int k = 0; k < 2; ++k) dst[m][k] = *(const PG8_LAS bf16x8*)(lds + PG8_SA(b, h) + aoff + m * 2048 + k * 1024); } while (0)
; #define PG8_MMA(ai, bj, At, Bt) do { __builtin_amdgcn_s_setprio(1); _Pragma("unroll") for (int m = 0; m < 4; ++m) _Pragma("unroll") for (int n = 0; n < 2; ++n) _Pragma("unroll") for (int k = 0; k < 2; ++k) \
;         acc[ai][bj][m][n] = __builtin_amdgcn_mfma_f32_16x16x32_bf16(Bt[n][k], At[m][k], acc[ai][bj][m][n], 0, 0, 0); __builtin_amdgcn_s_setprio(0); } while (0)
; #define PG8_WAIT_V(n) asm volatile("s_waitcnt vmcnt(" #n ")" ::: "memory")
; #define PG8_WAIT_L(n) asm volatile("s_waitcnt lgkmcnt(" #n ")" ::: "memory")
; #define PG8_BAR __builtin_amdgcn_s_barrier()
; #define PG8_SCHED __builtin_amdgcn_sched_barrier(0)
; template <class Epi, class Sched, bool ALIGN_EPI = false, bool SP2 = false>
; __device__ __forceinline__ void gemm_phase(PG8_LAS unsigned char* lds, const Gemm g, const Sched& S, const Epi& E) {
;     ...
;             PG8_LDA(At, 1, 1); PG8_STAGE(PG8_SB(1, 0), b3, voffB); PG8_STAGE(PG8_SB(1, 1), b3 + hstep, voffB); PG8_STAGE(PG8_SA(1, 0), a3, voffA);
;             PG8_WAIT_V(8); PG8_WAIT_L(0); PG8_BAR; PG8_MMA(1, 0, At, B0); PG8_MMA(1, 1, At, B1); PG8_BAR; PG8_SCHED;
	s_add_i32 s82, s85, s87
	s_mov_b32 m0, s82
	ds_read_b128 v[186:189], v162 offset:49152
	ds_read_b128 v[190:193], v162 offset:50176
	ds_read_b128 v[194:197], v162 offset:51200
	ds_read_b128 v[198:201], v162 offset:52224
	ds_read_b128 v[202:205], v162 offset:53248
	ds_read_b128 v[208:211], v162 offset:54272
	ds_read_b128 v[212:215], v162 offset:55296
	ds_read_b128 v[216:219], v162 offset:56320
	s_add_u32 s98, s8, s26
	s_addc_u32 s99, s9, s27
	global_load_lds_dwordx4 v132, s[98:99]
	s_add_i32 m0, s82, 0x2000
	s_add_u32 s8, s8, 0x40080
	v_lshl_add_u64 v[220:221], v[222:223], 0, s[26:27]
	s_addc_u32 s9, s9, 0
	s_add_i32 s82, vcc_lo, s87
	global_load_lds_dwordx4 v[220:221], off
	s_mov_b32 m0, s82
	s_nop 0
	global_load_lds_dwordx4 v132, s[8:9]
	s_add_i32 m0, s82, 0x2000
	s_nop 0
	global_load_lds_dwordx4 v136, s[8:9]
	v_lshl_add_u64 v[220:221], v[224:225], 0, s[26:27]
	s_mov_b32 m0, s92
	s_nop 0
	global_load_lds_dwordx4 v[220:221], off
	v_lshl_add_u64 v[220:221], v[226:227], 0, s[26:27]
	s_mov_b32 m0, s93
	s_nop 0
	global_load_lds_dwordx4 v[220:221], off
	s_waitcnt vmcnt(8)
	s_waitcnt lgkmcnt(0)
	s_barrier
	s_setprio 1
	s_waitcnt lgkmcnt(0)
	v_mfma_f32_16x16x32_bf16 v[94:97], v[146:149], v[186:189], v[94:97]
	v_mfma_f32_16x16x32_bf16 v[90:93], v[154:157], v[186:189], v[90:93]
	v_mfma_f32_16x16x32_bf16 v[86:89], v[146:149], v[194:197], v[86:89]
	v_mfma_f32_16x16x32_bf16 v[82:85], v[154:157], v[194:197], v[82:85]
	v_mfma_f32_16x16x32_bf16 v[78:81], v[146:149], v[202:205], v[78:81]
	v_mfma_f32_16x16x32_bf16 v[74:77], v[154:157], v[202:205], v[74:77]
	v_mfma_f32_16x16x32_bf16 v[70:73], v[146:149], v[212:215], v[70:73]
	v_mfma_f32_16x16x32_bf16 v[66:69], v[154:157], v[212:215], v[66:69]
	v_mfma_f32_16x16x32_bf16 v[94:97], v[150:153], v[190:193], v[94:97]
	v_mfma_f32_16x16x32_bf16 v[90:93], v[166:169], v[190:193], v[90:93]
	v_mfma_f32_16x16x32_bf16 v[86:89], v[150:153], v[198:201], v[86:89]
	v_mfma_f32_16x16x32_bf16 v[82:85], v[166:169], v[198:201], v[82:85]
	v_mfma_f32_16x16x32_bf16 v[78:81], v[150:153], v[208:211], v[78:81]
	v_mfma_f32_16x16x32_bf16 v[74:77], v[166:169], v[208:211], v[74:77]
	v_mfma_f32_16x16x32_bf16 v[70:73], v[150:153], v[216:219], v[70:73]
	v_mfma_f32_16x16x32_bf16 v[66:69], v[166:169], v[216:219], v[66:69]
	s_setprio 0
	s_setprio 1
	v_mfma_f32_16x16x32_bf16 v[30:33], v[170:173], v[186:189], v[30:33]
	v_mfma_f32_16x16x32_bf16 v[26:29], v[178:181], v[186:189], v[26:29]
	v_mfma_f32_16x16x32_bf16 v[22:25], v[170:173], v[194:197], v[22:25]
	v_mfma_f32_16x16x32_bf16 v[18:21], v[178:181], v[194:197], v[18:21]
	v_mfma_f32_16x16x32_bf16 v[14:17], v[170:173], v[202:205], v[14:17]
	v_mfma_f32_16x16x32_bf16 v[10:13], v[178:181], v[202:205], v[10:13]
	v_mfma_f32_16x16x32_bf16 v[6:9], v[170:173], v[212:215], v[6:9]
	v_mfma_f32_16x16x32_bf16 v[2:5], v[178:181], v[212:215], v[2:5]
	v_mfma_f32_16x16x32_bf16 v[30:33], v[174:177], v[190:193], v[30:33]
	v_mfma_f32_16x16x32_bf16 v[26:29], v[182:185], v[190:193], v[26:29]
	v_mfma_f32_16x16x32_bf16 v[22:25], v[174:177], v[198:201], v[22:25]
	v_mfma_f32_16x16x32_bf16 v[18:21], v[182:185], v[198:201], v[18:21]
	v_mfma_f32_16x16x32_bf16 v[14:17], v[174:177], v[208:211], v[14:17]
	v_mfma_f32_16x16x32_bf16 v[10:13], v[182:185], v[208:211], v[10:13]
	v_mfma_f32_16x16x32_bf16 v[6:9], v[174:177], v[216:219], v[6:9]
	v_mfma_f32_16x16x32_bf16 v[2:5], v[182:185], v[216:219], v[2:5]
	s_setprio 0
	s_add_i32 s84, s84, 2
	s_add_u32 s6, s6, 0x100
	s_addc_u32 s7, s7, 0
	s_add_u32 s73, s73, 0x100
	s_addc_u32 s75, s75, 0
	s_cmp_gt_u32 s84, 13
	s_barrier

;     __device__ __forceinline__ void operator()(const f32x4 (&acc)[2][2][4][2], const Unit& u, int wr, int wc, int fr, int fq) const {
;     ...
;                     const int row = row0 + ai * HALF + m * 16; const float rs = rsc ? rsc[row - rbase] : rstd[row];
;                     float v[8];
; #pragma unroll
;                     for (int i = 0; i < 4; ++i) { v[i] = acc[ai][bj][m][0][i] * rs; v[4 + i] = acc[ai][bj][m][1][i] * rs; }
;                     if (seg == 0) {
; #pragma unroll
;                         for (int i = 0; i < 8; ++i) v[i] = v[i] * __builtin_amdgcn_rcpf(1.0f + __expf(-v[i])) * 0.08838834764831845f;
;                     } else if (seg == 1) {
; #pragma unroll
;                         for (int i = 0; i < 8; ++i) { const float s = __builtin_amdgcn_rcpf(1.0f + __expf(-v[i])); v[i] = __logf(lb[i] + (1.0f - lb[i]) * s); }
;                     } else if (seg == 3) {
; #pragma unroll
;                         for (int i = 0; i < 8; ++i) v[i] = v[i] * __builtin_amdgcn_rcpf(1.0f + __expf(-v[i]));
.LBB0_115:
	v_lshl_add_u32 v148, s0, 8, v1
	s_mov_b64 s[0:1], -1
	s_and_b64 vcc, exec, s[36:37]
	v_ashrrev_i32_e32 v149, 31, v148
	s_cbranch_vccz .LBB0_117
	v_lshl_add_u64 v[150:151], v[148:149], 2, s[24:25]
	global_load_dword v150, v[150:151], off
	s_waitcnt vmcnt(0)
	s_mov_b64 s[0:1], 0
.LBB0_117:
	v_subrev_u32_e32 v147, s71, v148
	s_andn2_b64 vcc, exec, s[0:1]
	v_lshl_add_u32 v165, v147, 2, s86
	s_cbranch_vccnz .LBB0_119
	ds_read_b32 v228, v165
	ds_read_b32 v229, v165 offset:64
	ds_read_b32 v230, v165 offset:128
	ds_read_b32 v231, v165 offset:192
	ds_read_b32 v232, v165 offset:512
	ds_read_b32 v233, v165 offset:576
	ds_read_b32 v234, v165 offset:640
	ds_read_b32 v235, v165 offset:704
	s_waitcnt lgkmcnt(0)
	v_mov_b32_e32 v150, v228
.LBB0_119:
	s_cmp_gt_u32 s80, 1
	s_cselect_b64 s[84:85], -1, 0
	s_cmp_eq_u32 s73, 3
	s_cselect_b64 s[82:83], -1, 0
	s_waitcnt lgkmcnt(0)
	v_pk_mul_f32 v[126:127], v[126:127], v[150:151] op_sel_hi:[1,0]
	v_pk_mul_f32 v[122:123], v[122:123], v[150:151] op_sel_hi:[1,0]
	v_pk_mul_f32 v[128:129], v[128:129], v[150:151] op_sel_hi:[1,0]
	v_pk_mul_f32 v[124:125], v[124:125], v[150:151] op_sel_hi:[1,0]
	s_mov_b64 s[0:1], -1
	s_and_b64 vcc, exec, s[84:85]
	s_cbranch_vccz .LBB0_126
	s_and_b64 vcc, exec, s[6:7]
	s_cbranch_vccz .LBB0_123
	s_andn2_b64 vcc, exec, s[82:83]
	s_cbranch_vccnz .LBB0_328
	v_pk_mul_f32 v[150:151], v[126:127], s[100:101] op_sel_hi:[1,0]
	v_pk_mul_f32 v[152:153], v[128:129], s[100:101] op_sel_hi:[1,0]
	v_pk_mul_f32 v[154:155], v[122:123], s[100:101] op_sel_hi:[1,0]
	v_pk_mul_f32 v[156:157], v[124:125], s[100:101] op_sel_hi:[1,0]
	v_exp_f32_e32 v150, v150
	v_exp_f32_e32 v151, v151
	v_exp_f32_e32 v152, v152
	v_exp_f32_e32 v153, v153
	v_exp_f32_e32 v154, v154
	v_exp_f32_e32 v155, v155
	v_exp_f32_e32 v156, v156
	v_exp_f32_e32 v157, v157
	v_pk_add_f32 v[150:151], v[150:151], s[98:99] op_sel_hi:[1,0]
	v_pk_add_f32 v[152:153], v[152:153], s[98:99] op_sel_hi:[1,0]
	v_pk_add_f32 v[154:155], v[154:155], s[98:99] op_sel_hi:[1,0]
	v_pk_add_f32 v[156:157], v[156:157], s[98:99] op_sel_hi:[1,0]
	v_rcp_f32_e32 v150, v150
	v_rcp_f32_e32 v151, v151
	v_rcp_f32_e32 v152, v152
	v_rcp_f32_e32 v153, v153
	v_rcp_f32_e32 v154, v154
	v_rcp_f32_e32 v155, v155
	v_rcp_f32_e32 v156, v156
	v_rcp_f32_e32 v157, v157
	s_mov_b64 s[0:1], 0
	v_pk_mul_f32 v[150:151], v[126:127], v[150:151]
	v_pk_mul_f32 v[152:153], v[128:129], v[152:153]
	v_pk_mul_f32 v[154:155], v[122:123], v[154:155]
	v_pk_mul_f32 v[156:157], v[124:125], v[156:157]

; __device__ __forceinline__ unsigned cvt_pk_bf16(float lo, float hi) { f32x2 v = {lo, hi}; return __builtin_bit_cast(unsigned, __builtin_convertvector(v, nbf16x2e)); }
;     __device__ __forceinline__ void operator()(const f32x4 (&acc)[2][2][4][2], const Unit& u, int wr, int wc, int fr, int fq) const {
;     ...
;                     const int row = row0 + ai * HALF + m * 16; const float rs = rsc ? rsc[row - rbase] : rstd[row];
;                     float v[8];
; #pragma unroll
;                     for (int i = 0; i < 4; ++i) { v[i] = acc[ai][bj][m][0][i] * rs; v[4 + i] = acc[ai][bj][m][1][i] * rs; }
;                     if (seg == 0) {
; #pragma unroll
;                         for (int i = 0; i < 8; ++i) v[i] = v[i] * __builtin_amdgcn_rcpf(1.0f + __expf(-v[i])) * 0.08838834764831845f;
;                     } else if (seg == 1) {
; #pragma unroll
;                         for (int i = 0; i < 8; ++i) { const float s = __builtin_amdgcn_rcpf(1.0f + __expf(-v[i])); v[i] = __logf(lb[i] + (1.0f - lb[i]) * s); }
;                     } else if (seg == 3) {
; #pragma unroll
;                         for (int i = 0; i < 8; ++i) v[i] = v[i] * __builtin_amdgcn_rcpf(1.0f + __expf(-v[i]));
;                     }
;                     u32x4 w; w.x = cvt_pk_bf16(v[0], v[1]); w.y = cvt_pk_bf16(v[2], v[3]); w.z = cvt_pk_bf16(v[4], v[5]); w.w = cvt_pk_bf16(v[6], v[7]);
;                     *(u32x4*)(O + (size_t)row * 2816 + col0) = w;
.LBB0_128:
	v_mov_b64_e32 v[122:123], s[34:35]
	v_ashrrev_i32_e32 v147, 31, v146
	v_mad_i64_i32 v[122:123], s[0:1], v148, s67, v[122:123]
	v_lshl_add_u64 v[124:125], v[146:147], 1, v[122:123]
	v_or_b32_e32 v122, 16, v148
	v_cvt_pk_bf16_f32 v126, v150, v151
	v_cvt_pk_bf16_f32 v127, v152, v153
	v_cvt_pk_bf16_f32 v128, v154, v155
	v_cvt_pk_bf16_f32 v129, v156, v157
	s_mov_b64 s[0:1], -1
	s_and_b64 vcc, exec, s[36:37]
	v_ashrrev_i32_e32 v123, 31, v122
	global_store_dwordx4 v[124:125], v[126:129], off
	s_cbranch_vccz .LBB0_130
	s_nop 0
	v_lshl_add_u64 v[126:127], v[122:123], 2, s[24:25]
	global_load_dword v126, v[126:127], off
	s_waitcnt vmcnt(0)
	s_mov_b64 s[0:1], 0
.LBB0_130:
	s_andn2_b64 vcc, exec, s[0:1]
	s_cbranch_vccnz .LBB0_132
	v_mov_b32_e32 v126, v229
.LBB0_132:
	s_waitcnt lgkmcnt(0)
	v_pk_mul_f32 v[118:119], v[118:119], v[126:127] op_sel_hi:[1,0]
	v_pk_mul_f32 v[114:115], v[114:115], v[126:127] op_sel_hi:[1,0]
	v_pk_mul_f32 v[120:121], v[120:121], v[126:127] op_sel_hi:[1,0]
	v_pk_mul_f32 v[116:117], v[116:117], v[126:127] op_sel_hi:[1,0]
	v_cndmask_b32_e64 v126, 0, 1, s[84:85]
	v_cmp_ne_u32_e64 s[8:9], 1, v126
	v_cndmask_b32_e64 v126, 0, 1, s[6:7]
	s_mov_b64 s[0:1], -1
	s_andn2_b64 vcc, exec, s[84:85]
	v_cmp_ne_u32_e64 s[6:7], 1, v126
	s_cbranch_vccnz .LBB0_139
	s_and_b64 vcc, exec, s[6:7]
	s_cbranch_vccnz .LBB0_136
	s_andn2_b64 vcc, exec, s[82:83]
	s_cbranch_vccnz .LBB0_329
	v_pk_mul_f32 v[126:127], v[118:119], s[100:101] op_sel_hi:[1,0]
	v_pk_mul_f32 v[128:129], v[120:121], s[100:101] op_sel_hi:[1,0]
	v_pk_mul_f32 v[150:151], v[114:115], s[100:101] op_sel_hi:[1,0]
	v_pk_mul_f32 v[152:153], v[116:117], s[100:101] op_sel_hi:[1,0]
	v_exp_f32_e32 v126, v126
	v_exp_f32_e32 v127, v127
	v_exp_f32_e32 v128, v128
	v_exp_f32_e32 v129, v129
	v_exp_f32_e32 v150, v150
	v_exp_f32_e32 v151, v151
	v_exp_f32_e32 v152, v152
	v_exp_f32_e32 v153, v153
	v_pk_add_f32 v[126:127], v[126:127], s[98:99] op_sel_hi:[1,0]
	v_pk_add_f32 v[128:129], v[128:129], s[98:99] op_sel_hi:[1,0]
	v_pk_add_f32 v[150:151], v[150:151], s[98:99] op_sel_hi:[1,0]
	v_pk_add_f32 v[152:153], v[152:153], s[98:99] op_sel_hi:[1,0]
	v_rcp_f32_e32 v126, v126
	v_rcp_f32_e32 v127, v127
	v_rcp_f32_e32 v128, v128
	v_rcp_f32_e32 v129, v129
	v_rcp_f32_e32 v150, v150
	v_rcp_f32_e32 v151, v151
	v_rcp_f32_e32 v152, v152
	v_rcp_f32_e32 v153, v153
	s_nop 0
	v_pk_mul_f32 v[126:127], v[118:119], v[126:127]
	v_pk_mul_f32 v[128:129], v[120:121], v[128:129]
	v_pk_mul_f32 v[150:151], v[114:115], v[150:151]
	v_pk_mul_f32 v[152:153], v[116:117], v[152:153]
	s_mov_b64 s[0:1], 0

; __device__ __forceinline__ unsigned cvt_pk_bf16(float lo, float hi) { f32x2 v = {lo, hi}; return __builtin_bit_cast(unsigned, __builtin_convertvector(v, nbf16x2e)); }
;     __device__ __forceinline__ void operator()(const f32x4 (&acc)[2][2][4][2], const Unit& u, int wr, int wc, int fr, int fq) const {
;     ...
;                     const int row = row0 + ai * HALF + m * 16; const float rs = rsc ? rsc[row - rbase] : rstd[row];
;                     float v[8];
; #pragma unroll
;                     for (int i = 0; i < 4; ++i) { v[i] = acc[ai][bj][m][0][i] * rs; v[4 + i] = acc[ai][bj][m][1][i] * rs; }
;                     if (seg == 0) {
; #pragma unroll
;                         for (int i = 0; i < 8; ++i) v[i] = v[i] * __builtin_amdgcn_rcpf(1.0f + __expf(-v[i])) * 0.08838834764831845f;
;                     } else if (seg == 1) {
; #pragma unroll
;                         for (int i = 0; i < 8; ++i) { const float s = __builtin_amdgcn_rcpf(1.0f + __expf(-v[i])); v[i] = __logf(lb[i] + (1.0f - lb[i]) * s); }
;                     } else if (seg == 3) {
; #pragma unroll
;                         for (int i = 0; i < 8; ++i) v[i] = v[i] * __builtin_amdgcn_rcpf(1.0f + __expf(-v[i]));
;                     }
;                     u32x4 w; w.x = cvt_pk_bf16(v[0], v[1]); w.y = cvt_pk_bf16(v[2], v[3]); w.z = cvt_pk_bf16(v[4], v[5]); w.w = cvt_pk_bf16(v[6], v[7]);
;                     *(u32x4*)(O + (size_t)row * 2816 + col0) = w;
.LBB0_141:
	v_mov_b64_e32 v[114:115], s[34:35]
	v_mad_i64_i32 v[114:115], s[0:1], v122, s67, v[114:115]
	v_lshl_add_u64 v[116:117], v[146:147], 1, v[114:115]
	v_or_b32_e32 v114, 32, v148
	v_cvt_pk_bf16_f32 v118, v126, v127
	v_cvt_pk_bf16_f32 v119, v128, v129
	v_cvt_pk_bf16_f32 v120, v150, v151
	v_cvt_pk_bf16_f32 v121, v152, v153
	s_mov_b64 s[0:1], -1
	s_and_b64 vcc, exec, s[36:37]
	v_ashrrev_i32_e32 v115, 31, v114
	global_store_dwordx4 v[116:117], v[118:121], off
	s_cbranch_vccz .LBB0_143
	s_nop 0
	v_lshl_add_u64 v[118:119], v[114:115], 2, s[24:25]
	global_load_dword v118, v[118:119], off
	s_waitcnt vmcnt(0)
	s_mov_b64 s[0:1], 0
.LBB0_143:
	s_andn2_b64 vcc, exec, s[0:1]
	s_cbranch_vccnz .LBB0_145
	v_mov_b32_e32 v118, v230
.LBB0_145:
	s_waitcnt lgkmcnt(0)
	v_pk_mul_f32 v[110:111], v[110:111], v[118:119] op_sel_hi:[1,0]
	v_pk_mul_f32 v[106:107], v[106:107], v[118:119] op_sel_hi:[1,0]
	v_pk_mul_f32 v[112:113], v[112:113], v[118:119] op_sel_hi:[1,0]
	v_pk_mul_f32 v[108:109], v[108:109], v[118:119] op_sel_hi:[1,0]
	s_and_b64 vcc, exec, s[8:9]
	s_mov_b64 s[0:1], -1
	s_cbranch_vccnz .LBB0_152
	s_and_b64 vcc, exec, s[6:7]
	s_cbranch_vccnz .LBB0_149
	s_andn2_b64 vcc, exec, s[82:83]
	s_cbranch_vccnz .LBB0_330
	v_pk_mul_f32 v[118:119], v[110:111], s[100:101] op_sel_hi:[1,0]
	v_pk_mul_f32 v[120:121], v[112:113], s[100:101] op_sel_hi:[1,0]
	v_pk_mul_f32 v[126:127], v[106:107], s[100:101] op_sel_hi:[1,0]
	v_pk_mul_f32 v[128:129], v[108:109], s[100:101] op_sel_hi:[1,0]
	v_exp_f32_e32 v118, v118
	v_exp_f32_e32 v119, v119
	v_exp_f32_e32 v120, v120
	v_exp_f32_e32 v121, v121
	v_exp_f32_e32 v126, v126
	v_exp_f32_e32 v127, v127
	v_exp_f32_e32 v128, v128
	v_exp_f32_e32 v129, v129
	v_pk_add_f32 v[118:119], v[118:119], s[98:99] op_sel_hi:[1,0]
	v_pk_add_f32 v[120:121], v[120:121], s[98:99] op_sel_hi:[1,0]
	v_pk_add_f32 v[126:127], v[126:127], s[98:99] op_sel_hi:[1,0]
	v_pk_add_f32 v[128:129], v[128:129], s[98:99] op_sel_hi:[1,0]
	v_rcp_f32_e32 v118, v118
	v_rcp_f32_e32 v119, v119
	v_rcp_f32_e32 v120, v120
	v_rcp_f32_e32 v121, v121
	v_rcp_f32_e32 v126, v126
	v_rcp_f32_e32 v127, v127
	v_rcp_f32_e32 v128, v128
	v_rcp_f32_e32 v129, v129
	s_nop 0
	v_pk_mul_f32 v[118:119], v[110:111], v[118:119]
	v_pk_mul_f32 v[120:121], v[112:113], v[120:121]
	v_pk_mul_f32 v[126:127], v[106:107], v[126:127]
	v_pk_mul_f32 v[128:129], v[108:109], v[128:129]
	s_mov_b64 s[0:1], 0

; __device__ __forceinline__ unsigned cvt_pk_bf16(float lo, float hi) { f32x2 v = {lo, hi}; return __builtin_bit_cast(unsigned, __builtin_convertvector(v, nbf16x2e)); }
;     __device__ __forceinline__ void operator()(const f32x4 (&acc)[2][2][4][2], const Unit& u, int wr, int wc, int fr, int fq) const {
;     ...
;                     const int row = row0 + ai * HALF + m * 16; const float rs = rsc ? rsc[row - rbase] : rstd[row];
;                     float v[8];
; #pragma unroll
;                     for (int i = 0; i < 4; ++i) { v[i] = acc[ai][bj][m][0][i] * rs; v[4 + i] = acc[ai][bj][m][1][i] * rs; }
;                     if (seg == 0) {
; #pragma unroll
;                         for (int i = 0; i < 8; ++i) v[i] = v[i] * __builtin_amdgcn_rcpf(1.0f + __expf(-v[i])) * 0.08838834764831845f;
;                     } else if (seg == 1) {
; #pragma unroll
;                         for (int i = 0; i < 8; ++i) { const float s = __builtin_amdgcn_rcpf(1.0f + __expf(-v[i])); v[i] = __logf(lb[i] + (1.0f - lb[i]) * s); }
;                     } else if (seg == 3) {
; #pragma unroll
;                         for (int i = 0; i < 8; ++i) v[i] = v[i] * __builtin_amdgcn_rcpf(1.0f + __expf(-v[i]));
;                     }
;                     u32x4 w; w.x = cvt_pk_bf16(v[0], v[1]); w.y = cvt_pk_bf16(v[2], v[3]); w.z = cvt_pk_bf16(v[4], v[5]); w.w = cvt_pk_bf16(v[6], v[7]);
;                     *(u32x4*)(O + (size_t)row * 2816 + col0) = w;
.LBB0_154:
	v_mov_b64_e32 v[106:107], s[34:35]
	v_mad_i64_i32 v[106:107], s[0:1], v114, s67, v[106:107]
	v_lshl_add_u64 v[108:109], v[146:147], 1, v[106:107]
	v_or_b32_e32 v106, 48, v148
	v_cvt_pk_bf16_f32 v110, v118, v119
	v_cvt_pk_bf16_f32 v111, v120, v121
	v_cvt_pk_bf16_f32 v112, v126, v127
	v_cvt_pk_bf16_f32 v113, v128, v129
	s_mov_b64 s[0:1], -1
	s_and_b64 vcc, exec, s[36:37]
	v_ashrrev_i32_e32 v107, 31, v106
	global_store_dwordx4 v[108:109], v[110:113], off
	s_cbranch_vccz .LBB0_156
	s_nop 0
	v_lshl_add_u64 v[110:111], v[106:107], 2, s[24:25]
	global_load_dword v110, v[110:111], off
	s_waitcnt vmcnt(0)
	s_mov_b64 s[0:1], 0
.LBB0_156:
	s_andn2_b64 vcc, exec, s[0:1]
	s_cbranch_vccnz .LBB0_158
	v_mov_b32_e32 v110, v231
.LBB0_158:
	s_waitcnt lgkmcnt(0)
	v_pk_mul_f32 v[102:103], v[102:103], v[110:111] op_sel_hi:[1,0]
	v_pk_mul_f32 v[98:99], v[98:99], v[110:111] op_sel_hi:[1,0]
	v_pk_mul_f32 v[104:105], v[104:105], v[110:111] op_sel_hi:[1,0]
	v_pk_mul_f32 v[100:101], v[100:101], v[110:111] op_sel_hi:[1,0]
	s_and_b64 vcc, exec, s[8:9]
	s_mov_b64 s[0:1], -1
	s_cbranch_vccnz .LBB0_165
	s_and_b64 vcc, exec, s[6:7]
	s_cbranch_vccnz .LBB0_162
	s_andn2_b64 vcc, exec, s[82:83]
	s_cbranch_vccnz .LBB0_331
	v_pk_mul_f32 v[110:111], v[102:103], s[100:101] op_sel_hi:[1,0]
	v_pk_mul_f32 v[112:113], v[104:105], s[100:101] op_sel_hi:[1,0]
	v_pk_mul_f32 v[118:119], v[98:99], s[100:101] op_sel_hi:[1,0]
	v_pk_mul_f32 v[120:121], v[100:101], s[100:101] op_sel_hi:[1,0]
	v_exp_f32_e32 v110, v110
	v_exp_f32_e32 v111, v111
	v_exp_f32_e32 v112, v112
	v_exp_f32_e32 v113, v113
	v_exp_f32_e32 v118, v118
	v_exp_f32_e32 v119, v119
	v_exp_f32_e32 v120, v120
	v_exp_f32_e32 v121, v121
	v_pk_add_f32 v[110:111], v[110:111], s[98:99] op_sel_hi:[1,0]
	v_pk_add_f32 v[112:113], v[112:113], s[98:99] op_sel_hi:[1,0]
	v_pk_add_f32 v[118:119], v[118:119], s[98:99] op_sel_hi:[1,0]
	v_pk_add_f32 v[120:121], v[120:121], s[98:99] op_sel_hi:[1,0]
	v_rcp_f32_e32 v110, v110
	v_rcp_f32_e32 v111, v111
	v_rcp_f32_e32 v112, v112
	v_rcp_f32_e32 v113, v113
	v_rcp_f32_e32 v118, v118
	v_rcp_f32_e32 v119, v119
	v_rcp_f32_e32 v120, v120
	v_rcp_f32_e32 v121, v121
	s_nop 0
	v_pk_mul_f32 v[110:111], v[102:103], v[110:111]
	v_pk_mul_f32 v[112:113], v[104:105], v[112:113]
	v_pk_mul_f32 v[118:119], v[98:99], v[118:119]
	v_pk_mul_f32 v[120:121], v[100:101], v[120:121]
	s_mov_b64 s[0:1], 0

; __device__ __forceinline__ unsigned cvt_pk_bf16(float lo, float hi) { f32x2 v = {lo, hi}; return __builtin_bit_cast(unsigned, __builtin_convertvector(v, nbf16x2e)); }
;     __device__ __forceinline__ void operator()(const f32x4 (&acc)[2][2][4][2], const Unit& u, int wr, int wc, int fr, int fq) const {
;     ...
;                     const int row = row0 + ai * HALF + m * 16; const float rs = rsc ? rsc[row - rbase] : rstd[row];
;                     float v[8];
; #pragma unroll
;                     for (int i = 0; i < 4; ++i) { v[i] = acc[ai][bj][m][0][i] * rs; v[4 + i] = acc[ai][bj][m][1][i] * rs; }
;                     if (seg == 0) {
; #pragma unroll
;                         for (int i = 0; i < 8; ++i) v[i] = v[i] * __builtin_amdgcn_rcpf(1.0f + __expf(-v[i])) * 0.08838834764831845f;
;                     } else if (seg == 1) {
; #pragma unroll
;                         for (int i = 0; i < 8; ++i) { const float s = __builtin_amdgcn_rcpf(1.0f + __expf(-v[i])); v[i] = __logf(lb[i] + (1.0f - lb[i]) * s); }
;                     } else if (seg == 3) {
; #pragma unroll
;                         for (int i = 0; i < 8; ++i) v[i] = v[i] * __builtin_amdgcn_rcpf(1.0f + __expf(-v[i]));
;                     }
;                     u32x4 w; w.x = cvt_pk_bf16(v[0], v[1]); w.y = cvt_pk_bf16(v[2], v[3]); w.z = cvt_pk_bf16(v[4], v[5]); w.w = cvt_pk_bf16(v[6], v[7]);
;                     *(u32x4*)(O + (size_t)row * 2816 + col0) = w;
.LBB0_167:
	v_mov_b64_e32 v[98:99], s[34:35]
	v_mad_i64_i32 v[98:99], s[0:1], v106, s67, v[98:99]
	v_lshl_add_u64 v[100:101], v[146:147], 1, v[98:99]
	v_add_u32_e32 v98, 0x80, v148
	v_cvt_pk_bf16_f32 v102, v110, v111
	v_cvt_pk_bf16_f32 v103, v112, v113
	v_cvt_pk_bf16_f32 v104, v118, v119
	v_cvt_pk_bf16_f32 v105, v120, v121
	s_mov_b64 s[0:1], -1
	s_and_b64 vcc, exec, s[36:37]
	v_ashrrev_i32_e32 v99, 31, v98
	global_store_dwordx4 v[100:101], v[102:105], off
	s_cbranch_vccz .LBB0_169
	s_nop 0
	v_lshl_add_u64 v[102:103], v[98:99], 2, s[24:25]
	global_load_dword v102, v[102:103], off
	s_waitcnt vmcnt(0)
	s_mov_b64 s[0:1], 0
.LBB0_169:
	s_andn2_b64 vcc, exec, s[0:1]
	s_cbranch_vccnz .LBB0_171
	v_mov_b32_e32 v102, v232
.LBB0_171:
	s_waitcnt lgkmcnt(0)
	v_pk_mul_f32 v[94:95], v[94:95], v[102:103] op_sel_hi:[1,0]
	v_pk_mul_f32 v[90:91], v[90:91], v[102:103] op_sel_hi:[1,0]
	v_pk_mul_f32 v[96:97], v[96:97], v[102:103] op_sel_hi:[1,0]
	v_pk_mul_f32 v[92:93], v[92:93], v[102:103] op_sel_hi:[1,0]
	s_and_b64 vcc, exec, s[8:9]
	s_mov_b64 s[0:1], -1
	s_cbranch_vccnz .LBB0_178
	s_and_b64 vcc, exec, s[6:7]
	s_cbranch_vccnz .LBB0_175
	s_andn2_b64 vcc, exec, s[82:83]
	s_cbranch_vccnz .LBB0_332
	v_pk_mul_f32 v[102:103], v[94:95], s[100:101] op_sel_hi:[1,0]
	v_pk_mul_f32 v[104:105], v[96:97], s[100:101] op_sel_hi:[1,0]
	v_pk_mul_f32 v[110:111], v[90:91], s[100:101] op_sel_hi:[1,0]
	v_pk_mul_f32 v[112:113], v[92:93], s[100:101] op_sel_hi:[1,0]
	v_exp_f32_e32 v102, v102
	v_exp_f32_e32 v103, v103
	v_exp_f32_e32 v104, v104
	v_exp_f32_e32 v105, v105
	v_exp_f32_e32 v110, v110
	v_exp_f32_e32 v111, v111
	v_exp_f32_e32 v112, v112
	v_exp_f32_e32 v113, v113
	v_pk_add_f32 v[102:103], v[102:103], s[98:99] op_sel_hi:[1,0]
	v_pk_add_f32 v[104:105], v[104:105], s[98:99] op_sel_hi:[1,0]
	v_pk_add_f32 v[110:111], v[110:111], s[98:99] op_sel_hi:[1,0]
	v_pk_add_f32 v[112:113], v[112:113], s[98:99] op_sel_hi:[1,0]
	v_rcp_f32_e32 v102, v102
	v_rcp_f32_e32 v103, v103
	v_rcp_f32_e32 v104, v104
	v_rcp_f32_e32 v105, v105
	v_rcp_f32_e32 v110, v110
	v_rcp_f32_e32 v111, v111
	v_rcp_f32_e32 v112, v112
	v_rcp_f32_e32 v113, v113
	s_nop 0
	v_pk_mul_f32 v[102:103], v[94:95], v[102:103]
	v_pk_mul_f32 v[104:105], v[96:97], v[104:105]
	v_pk_mul_f32 v[110:111], v[90:91], v[110:111]
	v_pk_mul_f32 v[112:113], v[92:93], v[112:113]
	s_mov_b64 s[0:1], 0

; __device__ __forceinline__ unsigned cvt_pk_bf16(float lo, float hi) { f32x2 v = {lo, hi}; return __builtin_bit_cast(unsigned, __builtin_convertvector(v, nbf16x2e)); }
;     __device__ __forceinline__ void operator()(const f32x4 (&acc)[2][2][4][2], const Unit& u, int wr, int wc, int fr, int fq) const {
;     ...
;                     const int row = row0 + ai * HALF + m * 16; const float rs = rsc ? rsc[row - rbase] : rstd[row];
;                     float v[8];
; #pragma unroll
;                     for (int i = 0; i < 4; ++i) { v[i] = acc[ai][bj][m][0][i] * rs; v[4 + i] = acc[ai][bj][m][1][i] * rs; }
;                     if (seg == 0) {
; #pragma unroll
;                         for (int i = 0; i < 8; ++i) v[i] = v[i] * __builtin_amdgcn_rcpf(1.0f + __expf(-v[i])) * 0.08838834764831845f;
;                     } else if (seg == 1) {
; #pragma unroll
;                         for (int i = 0; i < 8; ++i) { const float s = __builtin_amdgcn_rcpf(1.0f + __expf(-v[i])); v[i] = __logf(lb[i] + (1.0f - lb[i]) * s); }
;                     } else if (seg == 3) {
; #pragma unroll
;                         for (int i = 0; i < 8; ++i) v[i] = v[i] * __builtin_amdgcn_rcpf(1.0f + __expf(-v[i]));
;                     }
;                     u32x4 w; w.x = cvt_pk_bf16(v[0], v[1]); w.y = cvt_pk_bf16(v[2], v[3]); w.z = cvt_pk_bf16(v[4], v[5]); w.w = cvt_pk_bf16(v[6], v[7]);
;                     *(u32x4*)(O + (size_t)row * 2816 + col0) = w;
.LBB0_180:
	v_mov_b64_e32 v[90:91], s[34:35]
	v_mad_i64_i32 v[90:91], s[0:1], v98, s67, v[90:91]
	v_lshl_add_u64 v[92:93], v[146:147], 1, v[90:91]
	v_add_u32_e32 v90, 0x90, v148
	v_cvt_pk_bf16_f32 v94, v102, v103
	v_cvt_pk_bf16_f32 v95, v104, v105
	v_cvt_pk_bf16_f32 v96, v110, v111
	v_cvt_pk_bf16_f32 v97, v112, v113
	s_mov_b64 s[0:1], -1
	s_and_b64 vcc, exec, s[36:37]
	v_ashrrev_i32_e32 v91, 31, v90
	global_store_dwordx4 v[92:93], v[94:97], off
	s_cbranch_vccz .LBB0_182
	s_nop 0
	v_lshl_add_u64 v[94:95], v[90:91], 2, s[24:25]
	global_load_dword v94, v[94:95], off
	s_waitcnt vmcnt(0)
	s_mov_b64 s[0:1], 0
.LBB0_182:
	s_andn2_b64 vcc, exec, s[0:1]
	s_cbranch_vccnz .LBB0_184
	v_mov_b32_e32 v94, v233
.LBB0_184:
	s_waitcnt lgkmcnt(0)
	v_pk_mul_f32 v[86:87], v[86:87], v[94:95] op_sel_hi:[1,0]
	v_pk_mul_f32 v[82:83], v[82:83], v[94:95] op_sel_hi:[1,0]
	v_pk_mul_f32 v[88:89], v[88:89], v[94:95] op_sel_hi:[1,0]
	v_pk_mul_f32 v[84:85], v[84:85], v[94:95] op_sel_hi:[1,0]
	s_and_b64 vcc, exec, s[8:9]
	s_mov_b64 s[0:1], -1
	s_cbranch_vccnz .LBB0_191
	s_and_b64 vcc, exec, s[6:7]
	s_cbranch_vccnz .LBB0_188
	s_andn2_b64 vcc, exec, s[82:83]
	s_cbranch_vccnz .LBB0_333
	v_pk_mul_f32 v[94:95], v[86:87], s[100:101] op_sel_hi:[1,0]
	v_pk_mul_f32 v[96:97], v[88:89], s[100:101] op_sel_hi:[1,0]
	v_pk_mul_f32 v[102:103], v[82:83], s[100:101] op_sel_hi:[1,0]
	v_pk_mul_f32 v[104:105], v[84:85], s[100:101] op_sel_hi:[1,0]
	v_exp_f32_e32 v94, v94
	v_exp_f32_e32 v95, v95
	v_exp_f32_e32 v96, v96
	v_exp_f32_e32 v97, v97
	v_exp_f32_e32 v102, v102
	v_exp_f32_e32 v103, v103
	v_exp_f32_e32 v104, v104
	v_exp_f32_e32 v105, v105
	v_pk_add_f32 v[94:95], v[94:95], s[98:99] op_sel_hi:[1,0]
	v_pk_add_f32 v[96:97], v[96:97], s[98:99] op_sel_hi:[1,0]
	v_pk_add_f32 v[102:103], v[102:103], s[98:99] op_sel_hi:[1,0]
	v_pk_add_f32 v[104:105], v[104:105], s[98:99] op_sel_hi:[1,0]
	v_rcp_f32_e32 v94, v94
	v_rcp_f32_e32 v95, v95
	v_rcp_f32_e32 v96, v96
	v_rcp_f32_e32 v97, v97
	v_rcp_f32_e32 v102, v102
	v_rcp_f32_e32 v103, v103
	v_rcp_f32_e32 v104, v104
	v_rcp_f32_e32 v105, v105
	s_nop 0
	v_pk_mul_f32 v[94:95], v[86:87], v[94:95]
	v_pk_mul_f32 v[96:97], v[88:89], v[96:97]
	v_pk_mul_f32 v[102:103], v[82:83], v[102:103]
	v_pk_mul_f32 v[104:105], v[84:85], v[104:105]
	s_mov_b64 s[0:1], 0

; __device__ __forceinline__ unsigned cvt_pk_bf16(float lo, float hi) { f32x2 v = {lo, hi}; return __builtin_bit_cast(unsigned, __builtin_convertvector(v, nbf16x2e)); }
;     __device__ __forceinline__ void operator()(const f32x4 (&acc)[2][2][4][2], const Unit& u, int wr, int wc, int fr, int fq) const {
;     ...
;                     const int row = row0 + ai * HALF + m * 16; const float rs = rsc ? rsc[row - rbase] : rstd[row];
;                     float v[8];
; #pragma unroll
;                     for (int i = 0; i < 4; ++i) { v[i] = acc[ai][bj][m][0][i] * rs; v[4 + i] = acc[ai][bj][m][1][i] * rs; }
;                     if (seg == 0) {
; #pragma unroll
;                         for (int i = 0; i < 8; ++i) v[i] = v[i] * __builtin_amdgcn_rcpf(1.0f + __expf(-v[i])) * 0.08838834764831845f;
;                     } else if (seg == 1) {
; #pragma unroll
;                         for (int i = 0; i < 8; ++i) { const float s = __builtin_amdgcn_rcpf(1.0f + __expf(-v[i])); v[i] = __logf(lb[i] + (1.0f - lb[i]) * s); }
;                     } else if (seg == 3) {
; #pragma unroll
;                         for (int i = 0; i < 8; ++i) v[i] = v[i] * __builtin_amdgcn_rcpf(1.0f + __expf(-v[i]));
;                     }
;                     u32x4 w; w.x = cvt_pk_bf16(v[0], v[1]); w.y = cvt_pk_bf16(v[2], v[3]); w.z = cvt_pk_bf16(v[4], v[5]); w.w = cvt_pk_bf16(v[6], v[7]);
;                     *(u32x4*)(O + (size_t)row * 2816 + col0) = w;
.LBB0_193:
	v_mov_b64_e32 v[82:83], s[34:35]
	v_mad_i64_i32 v[82:83], s[0:1], v90, s67, v[82:83]
	v_lshl_add_u64 v[84:85], v[146:147], 1, v[82:83]
	v_add_u32_e32 v82, 0xa0, v148
	v_cvt_pk_bf16_f32 v86, v94, v95
	v_cvt_pk_bf16_f32 v87, v96, v97
	v_cvt_pk_bf16_f32 v88, v102, v103
	v_cvt_pk_bf16_f32 v89, v104, v105
	s_mov_b64 s[0:1], -1
	s_and_b64 vcc, exec, s[36:37]
	v_ashrrev_i32_e32 v83, 31, v82
	global_store_dwordx4 v[84:85], v[86:89], off
	s_cbranch_vccz .LBB0_195
	s_nop 0
	v_lshl_add_u64 v[86:87], v[82:83], 2, s[24:25]
	global_load_dword v86, v[86:87], off
	s_waitcnt vmcnt(0)
	s_mov_b64 s[0:1], 0
.LBB0_195:
	s_andn2_b64 vcc, exec, s[0:1]
	s_cbranch_vccnz .LBB0_197
	v_mov_b32_e32 v86, v234
.LBB0_197:
	s_waitcnt lgkmcnt(0)
	v_pk_mul_f32 v[78:79], v[78:79], v[86:87] op_sel_hi:[1,0]
	v_pk_mul_f32 v[74:75], v[74:75], v[86:87] op_sel_hi:[1,0]
	v_pk_mul_f32 v[80:81], v[80:81], v[86:87] op_sel_hi:[1,0]
	v_pk_mul_f32 v[76:77], v[76:77], v[86:87] op_sel_hi:[1,0]
	s_and_b64 vcc, exec, s[8:9]
	s_mov_b64 s[0:1], -1
	s_cbranch_vccnz .LBB0_204
	s_and_b64 vcc, exec, s[6:7]
	s_cbranch_vccnz .LBB0_201
	s_andn2_b64 vcc, exec, s[82:83]
	s_cbranch_vccnz .LBB0_334
	v_pk_mul_f32 v[86:87], v[78:79], s[100:101] op_sel_hi:[1,0]
	v_pk_mul_f32 v[88:89], v[80:81], s[100:101] op_sel_hi:[1,0]
	v_pk_mul_f32 v[94:95], v[74:75], s[100:101] op_sel_hi:[1,0]
	v_pk_mul_f32 v[96:97], v[76:77], s[100:101] op_sel_hi:[1,0]
	v_exp_f32_e32 v86, v86
	v_exp_f32_e32 v87, v87
	v_exp_f32_e32 v88, v88
	v_exp_f32_e32 v89, v89
	v_exp_f32_e32 v94, v94
	v_exp_f32_e32 v95, v95
	v_exp_f32_e32 v96, v96
	v_exp_f32_e32 v97, v97
	v_pk_add_f32 v[86:87], v[86:87], s[98:99] op_sel_hi:[1,0]
	v_pk_add_f32 v[88:89], v[88:89], s[98:99] op_sel_hi:[1,0]
	v_pk_add_f32 v[94:95], v[94:95], s[98:99] op_sel_hi:[1,0]
	v_pk_add_f32 v[96:97], v[96:97], s[98:99] op_sel_hi:[1,0]
	v_rcp_f32_e32 v86, v86
	v_rcp_f32_e32 v87, v87
	v_rcp_f32_e32 v88, v88
	v_rcp_f32_e32 v89, v89
	v_rcp_f32_e32 v94, v94
	v_rcp_f32_e32 v95, v95
	v_rcp_f32_e32 v96, v96
	v_rcp_f32_e32 v97, v97
	s_nop 0
	v_pk_mul_f32 v[86:87], v[78:79], v[86:87]
	v_pk_mul_f32 v[88:89], v[80:81], v[88:89]
	v_pk_mul_f32 v[94:95], v[74:75], v[94:95]
	v_pk_mul_f32 v[96:97], v[76:77], v[96:97]
	s_mov_b64 s[0:1], 0

; __device__ __forceinline__ unsigned cvt_pk_bf16(float lo, float hi) { f32x2 v = {lo, hi}; return __builtin_bit_cast(unsigned, __builtin_convertvector(v, nbf16x2e)); }
;     __device__ __forceinline__ void operator()(const f32x4 (&acc)[2][2][4][2], const Unit& u, int wr, int wc, int fr, int fq) const {
;     ...
;                     const int row = row0 + ai * HALF + m * 16; const float rs = rsc ? rsc[row - rbase] : rstd[row];
;                     float v[8];
; #pragma unroll
;                     for (int i = 0; i < 4; ++i) { v[i] = acc[ai][bj][m][0][i] * rs; v[4 + i] = acc[ai][bj][m][1][i] * rs; }
;                     if (seg == 0) {
; #pragma unroll
;                         for (int i = 0; i < 8; ++i) v[i] = v[i] * __builtin_amdgcn_rcpf(1.0f + __expf(-v[i])) * 0.08838834764831845f;
;                     } else if (seg == 1) {
; #pragma unroll
;                         for (int i = 0; i < 8; ++i) { const float s = __builtin_amdgcn_rcpf(1.0f + __expf(-v[i])); v[i] = __logf(lb[i] + (1.0f - lb[i]) * s); }
;                     } else if (seg == 3) {
; #pragma unroll
;                         for (int i = 0; i < 8; ++i) v[i] = v[i] * __builtin_amdgcn_rcpf(1.0f + __expf(-v[i]));
;                     }
;                     u32x4 w; w.x = cvt_pk_bf16(v[0], v[1]); w.y = cvt_pk_bf16(v[2], v[3]); w.z = cvt_pk_bf16(v[4], v[5]); w.w = cvt_pk_bf16(v[6], v[7]);
;                     *(u32x4*)(O + (size_t)row * 2816 + col0) = w;
.LBB0_206:
	v_mov_b64_e32 v[74:75], s[34:35]
	v_mad_i64_i32 v[74:75], s[0:1], v82, s67, v[74:75]
	v_lshl_add_u64 v[76:77], v[146:147], 1, v[74:75]
	v_add_u32_e32 v74, 0xb0, v148
	v_cvt_pk_bf16_f32 v78, v86, v87
	v_cvt_pk_bf16_f32 v79, v88, v89
	v_cvt_pk_bf16_f32 v80, v94, v95
	v_cvt_pk_bf16_f32 v81, v96, v97
	s_mov_b64 s[0:1], -1
	s_and_b64 vcc, exec, s[36:37]
	v_ashrrev_i32_e32 v75, 31, v74
	global_store_dwordx4 v[76:77], v[78:81], off
	s_cbranch_vccz .LBB0_208
	s_nop 0
	v_lshl_add_u64 v[78:79], v[74:75], 2, s[24:25]
	global_load_dword v78, v[78:79], off
	s_waitcnt vmcnt(0)
	s_mov_b64 s[0:1], 0
.LBB0_208:
	s_andn2_b64 vcc, exec, s[0:1]
	s_cbranch_vccnz .LBB0_210
	v_mov_b32_e32 v78, v235
.LBB0_210:
	s_waitcnt lgkmcnt(0)
	v_pk_mul_f32 v[70:71], v[70:71], v[78:79] op_sel_hi:[1,0]
	v_pk_mul_f32 v[66:67], v[66:67], v[78:79] op_sel_hi:[1,0]
	v_pk_mul_f32 v[72:73], v[72:73], v[78:79] op_sel_hi:[1,0]
	v_pk_mul_f32 v[68:69], v[68:69], v[78:79] op_sel_hi:[1,0]
	s_and_b64 vcc, exec, s[8:9]
	s_mov_b64 s[0:1], -1
	s_cbranch_vccnz .LBB0_217
	s_and_b64 vcc, exec, s[6:7]
	s_cbranch_vccnz .LBB0_214
	s_andn2_b64 vcc, exec, s[82:83]
	s_cbranch_vccnz .LBB0_335
	v_pk_mul_f32 v[78:79], v[70:71], s[100:101] op_sel_hi:[1,0]
	v_pk_mul_f32 v[80:81], v[72:73], s[100:101] op_sel_hi:[1,0]
	v_pk_mul_f32 v[86:87], v[66:67], s[100:101] op_sel_hi:[1,0]
	v_pk_mul_f32 v[88:89], v[68:69], s[100:101] op_sel_hi:[1,0]
	v_exp_f32_e32 v78, v78
	v_exp_f32_e32 v79, v79
	v_exp_f32_e32 v80, v80
	v_exp_f32_e32 v81, v81
	v_exp_f32_e32 v86, v86
	v_exp_f32_e32 v87, v87
	v_exp_f32_e32 v88, v88
	v_exp_f32_e32 v89, v89
	v_pk_add_f32 v[78:79], v[78:79], s[98:99] op_sel_hi:[1,0]
	v_pk_add_f32 v[80:81], v[80:81], s[98:99] op_sel_hi:[1,0]
	v_pk_add_f32 v[86:87], v[86:87], s[98:99] op_sel_hi:[1,0]
	v_pk_add_f32 v[88:89], v[88:89], s[98:99] op_sel_hi:[1,0]
	v_rcp_f32_e32 v78, v78
	v_rcp_f32_e32 v79, v79
	v_rcp_f32_e32 v80, v80
	v_rcp_f32_e32 v81, v81
	v_rcp_f32_e32 v86, v86
	v_rcp_f32_e32 v87, v87
	v_rcp_f32_e32 v88, v88
	v_rcp_f32_e32 v89, v89
	s_nop 0
	v_pk_mul_f32 v[78:79], v[70:71], v[78:79]
	v_pk_mul_f32 v[80:81], v[72:73], v[80:81]
	v_pk_mul_f32 v[86:87], v[66:67], v[86:87]
	v_pk_mul_f32 v[88:89], v[68:69], v[88:89]
	s_mov_b64 s[0:1], 0

;     __device__ __forceinline__ void operator()(const f32x4 (&acc)[2][2][4][2], const Unit& u, int wr, int wc, int fr, int fq) const {
;     ...
;                     const int row = row0 + ai * HALF + m * 16; const float rs = rsc ? rsc[row - rbase] : rstd[row];
;                     float v[8];
; #pragma unroll
;                     for (int i = 0; i < 4; ++i) { v[i] = acc[ai][bj][m][0][i] * rs; v[4 + i] = acc[ai][bj][m][1][i] * rs; }
;                     if (seg == 0) {
; #pragma unroll
;                         for (int i = 0; i < 8; ++i) v[i] = v[i] * __builtin_amdgcn_rcpf(1.0f + __expf(-v[i])) * 0.08838834764831845f;
;                     } else if (seg == 1) {
; #pragma unroll
;                         for (int i = 0; i < 8; ++i) { const float s = __builtin_amdgcn_rcpf(1.0f + __expf(-v[i])); v[i] = __logf(lb[i] + (1.0f - lb[i]) * s); }
;                     } else if (seg == 3) {
; #pragma unroll
;                         for (int i = 0; i < 8; ++i) v[i] = v[i] * __builtin_amdgcn_rcpf(1.0f + __expf(-v[i]));
.LBB0_222:
	ds_read_b32 v228, v165
	ds_read_b32 v229, v165 offset:64
	ds_read_b32 v230, v165 offset:128
	ds_read_b32 v231, v165 offset:192
	ds_read_b32 v232, v165 offset:512
	ds_read_b32 v233, v165 offset:576
	ds_read_b32 v234, v165 offset:640
	ds_read_b32 v235, v165 offset:704
	s_waitcnt lgkmcnt(0)
	v_mov_b32_e32 v68, v228
.LBB0_223:
	s_cmp_gt_u32 s80, 1
	s_cselect_b64 s[84:85], -1, 0
	s_cmp_eq_u32 s73, 3
	s_waitcnt lgkmcnt(0)
	v_pk_mul_f32 v[62:63], v[62:63], v[68:69] op_sel_hi:[1,0]
	v_pk_mul_f32 v[58:59], v[58:59], v[68:69] op_sel_hi:[1,0]
	v_pk_mul_f32 v[64:65], v[64:65], v[68:69] op_sel_hi:[1,0]
	v_pk_mul_f32 v[60:61], v[60:61], v[68:69] op_sel_hi:[1,0]
	v_cndmask_b32_e64 v68, 0, 1, s[0:1]
	s_cselect_b64 s[82:83], -1, 0
	s_cmp_lt_u32 s80, 2
	s_mov_b64 s[8:9], -1
	v_cmp_ne_u32_e64 s[6:7], 1, v68
	s_cbranch_scc1 .LBB0_230
	s_and_b64 vcc, exec, s[6:7]
	s_mov_b64 s[0:1], -1
	s_cbranch_vccnz .LBB0_227
	s_andn2_b64 vcc, exec, s[82:83]
	s_cbranch_vccnz .LBB0_336
	v_pk_mul_f32 v[68:69], v[62:63], s[100:101] op_sel_hi:[1,0]
	v_pk_mul_f32 v[70:71], v[64:65], s[100:101] op_sel_hi:[1,0]
	v_pk_mul_f32 v[72:73], v[58:59], s[100:101] op_sel_hi:[1,0]
	v_pk_mul_f32 v[78:79], v[60:61], s[100:101] op_sel_hi:[1,0]
	v_exp_f32_e32 v68, v68
	v_exp_f32_e32 v69, v69
	v_exp_f32_e32 v70, v70
	v_exp_f32_e32 v71, v71
	v_exp_f32_e32 v72, v72
	v_exp_f32_e32 v73, v73
	v_exp_f32_e32 v78, v78
	v_exp_f32_e32 v79, v79
	v_pk_add_f32 v[68:69], v[68:69], s[98:99] op_sel_hi:[1,0]
	v_pk_add_f32 v[70:71], v[70:71], s[98:99] op_sel_hi:[1,0]
	v_pk_add_f32 v[72:73], v[72:73], s[98:99] op_sel_hi:[1,0]
	v_pk_add_f32 v[78:79], v[78:79], s[98:99] op_sel_hi:[1,0]
	v_rcp_f32_e32 v68, v68
	v_rcp_f32_e32 v69, v69
	v_rcp_f32_e32 v70, v70
	v_rcp_f32_e32 v71, v71
	v_rcp_f32_e32 v72, v72
	v_rcp_f32_e32 v73, v73
	v_rcp_f32_e32 v78, v78
	v_rcp_f32_e32 v79, v79
	s_nop 0
	v_pk_mul_f32 v[68:69], v[62:63], v[68:69]
	v_pk_mul_f32 v[70:71], v[64:65], v[70:71]
	v_pk_mul_f32 v[72:73], v[58:59], v[72:73]
	v_pk_mul_f32 v[78:79], v[60:61], v[78:79]
	s_mov_b64 s[0:1], 0

; __device__ __forceinline__ unsigned cvt_pk_bf16(float lo, float hi) { f32x2 v = {lo, hi}; return __builtin_bit_cast(unsigned, __builtin_convertvector(v, nbf16x2e)); }
;     __device__ __forceinline__ void operator()(const f32x4 (&acc)[2][2][4][2], const Unit& u, int wr, int wc, int fr, int fq) const {
;     ...
;                     const int row = row0 + ai * HALF + m * 16; const float rs = rsc ? rsc[row - rbase] : rstd[row];
;                     float v[8];
; #pragma unroll
;                     for (int i = 0; i < 4; ++i) { v[i] = acc[ai][bj][m][0][i] * rs; v[4 + i] = acc[ai][bj][m][1][i] * rs; }
;                     if (seg == 0) {
; #pragma unroll
;                         for (int i = 0; i < 8; ++i) v[i] = v[i] * __builtin_amdgcn_rcpf(1.0f + __expf(-v[i])) * 0.08838834764831845f;
;                     } else if (seg == 1) {
; #pragma unroll
;                         for (int i = 0; i < 8; ++i) { const float s = __builtin_amdgcn_rcpf(1.0f + __expf(-v[i])); v[i] = __logf(lb[i] + (1.0f - lb[i]) * s); }
;                     } else if (seg == 3) {
; #pragma unroll
;                         for (int i = 0; i < 8; ++i) v[i] = v[i] * __builtin_amdgcn_rcpf(1.0f + __expf(-v[i]));
;                     }
;                     u32x4 w; w.x = cvt_pk_bf16(v[0], v[1]); w.y = cvt_pk_bf16(v[2], v[3]); w.z = cvt_pk_bf16(v[4], v[5]); w.w = cvt_pk_bf16(v[6], v[7]);
;                     *(u32x4*)(O + (size_t)row * 2816 + col0) = w;
.LBB0_232:
	s_nop 0
	v_cvt_pk_bf16_f32 v58, v68, v69
	v_cvt_pk_bf16_f32 v59, v70, v71
	v_cvt_pk_bf16_f32 v60, v72, v73
	v_cvt_pk_bf16_f32 v61, v78, v79
	s_mov_b64 s[0:1], -1
	s_and_b64 vcc, exec, s[36:37]
	global_store_dwordx4 v[124:125], v[58:61], off offset:256
	s_cbranch_vccz .LBB0_234
	s_nop 0
	v_lshl_add_u64 v[58:59], v[122:123], 2, s[24:25]
	global_load_dword v58, v[58:59], off
	s_waitcnt vmcnt(0)
	s_mov_b64 s[0:1], 0
.LBB0_234:
	s_andn2_b64 vcc, exec, s[0:1]
	s_cbranch_vccnz .LBB0_236
	v_mov_b32_e32 v58, v229
.LBB0_236:
	s_waitcnt lgkmcnt(0)
	v_pk_mul_f32 v[54:55], v[54:55], v[58:59] op_sel_hi:[1,0]
	v_pk_mul_f32 v[50:51], v[50:51], v[58:59] op_sel_hi:[1,0]
	v_pk_mul_f32 v[56:57], v[56:57], v[58:59] op_sel_hi:[1,0]
	v_pk_mul_f32 v[52:53], v[52:53], v[58:59] op_sel_hi:[1,0]
	v_cndmask_b32_e64 v58, 0, 1, s[84:85]
	v_cmp_ne_u32_e64 s[8:9], 1, v58
	s_andn2_b64 vcc, exec, s[84:85]
	s_mov_b64 s[0:1], -1
	s_cbranch_vccnz .LBB0_243
	s_and_b64 vcc, exec, s[6:7]
	s_cbranch_vccnz .LBB0_240
	s_andn2_b64 vcc, exec, s[82:83]
	s_cbranch_vccnz .LBB0_337
	v_pk_mul_f32 v[58:59], v[54:55], s[100:101] op_sel_hi:[1,0]
	v_pk_mul_f32 v[60:61], v[56:57], s[100:101] op_sel_hi:[1,0]
	v_pk_mul_f32 v[62:63], v[50:51], s[100:101] op_sel_hi:[1,0]
	v_pk_mul_f32 v[64:65], v[52:53], s[100:101] op_sel_hi:[1,0]
	v_exp_f32_e32 v58, v58
	v_exp_f32_e32 v59, v59
	v_exp_f32_e32 v60, v60
	v_exp_f32_e32 v61, v61
	v_exp_f32_e32 v62, v62
	v_exp_f32_e32 v63, v63
	v_exp_f32_e32 v64, v64
	v_exp_f32_e32 v65, v65
	v_pk_add_f32 v[58:59], v[58:59], s[98:99] op_sel_hi:[1,0]
	v_pk_add_f32 v[60:61], v[60:61], s[98:99] op_sel_hi:[1,0]
	v_pk_add_f32 v[62:63], v[62:63], s[98:99] op_sel_hi:[1,0]
	v_pk_add_f32 v[64:65], v[64:65], s[98:99] op_sel_hi:[1,0]
	v_rcp_f32_e32 v58, v58
	v_rcp_f32_e32 v59, v59
	v_rcp_f32_e32 v60, v60
	v_rcp_f32_e32 v61, v61
	v_rcp_f32_e32 v62, v62
	v_rcp_f32_e32 v63, v63
	v_rcp_f32_e32 v64, v64
	v_rcp_f32_e32 v65, v65
	s_nop 0
	v_pk_mul_f32 v[58:59], v[54:55], v[58:59]
	v_pk_mul_f32 v[60:61], v[56:57], v[60:61]
	v_pk_mul_f32 v[62:63], v[50:51], v[62:63]
	v_pk_mul_f32 v[64:65], v[52:53], v[64:65]
	s_mov_b64 s[0:1], 0

; __device__ __forceinline__ unsigned cvt_pk_bf16(float lo, float hi) { f32x2 v = {lo, hi}; return __builtin_bit_cast(unsigned, __builtin_convertvector(v, nbf16x2e)); }
;     __device__ __forceinline__ void operator()(const f32x4 (&acc)[2][2][4][2], const Unit& u, int wr, int wc, int fr, int fq) const {
;     ...
;                     const int row = row0 + ai * HALF + m * 16; const float rs = rsc ? rsc[row - rbase] : rstd[row];
;                     float v[8];
; #pragma unroll
;                     for (int i = 0; i < 4; ++i) { v[i] = acc[ai][bj][m][0][i] * rs; v[4 + i] = acc[ai][bj][m][1][i] * rs; }
;                     if (seg == 0) {
; #pragma unroll
;                         for (int i = 0; i < 8; ++i) v[i] = v[i] * __builtin_amdgcn_rcpf(1.0f + __expf(-v[i])) * 0.08838834764831845f;
;                     } else if (seg == 1) {
; #pragma unroll
;                         for (int i = 0; i < 8; ++i) { const float s = __builtin_amdgcn_rcpf(1.0f + __expf(-v[i])); v[i] = __logf(lb[i] + (1.0f - lb[i]) * s); }
;                     } else if (seg == 3) {
; #pragma unroll
;                         for (int i = 0; i < 8; ++i) v[i] = v[i] * __builtin_amdgcn_rcpf(1.0f + __expf(-v[i]));
;                     }
;                     u32x4 w; w.x = cvt_pk_bf16(v[0], v[1]); w.y = cvt_pk_bf16(v[2], v[3]); w.z = cvt_pk_bf16(v[4], v[5]); w.w = cvt_pk_bf16(v[6], v[7]);
;                     *(u32x4*)(O + (size_t)row * 2816 + col0) = w;
.LBB0_245:
	s_nop 0
	v_cvt_pk_bf16_f32 v50, v58, v59
	v_cvt_pk_bf16_f32 v51, v60, v61
	v_cvt_pk_bf16_f32 v52, v62, v63
	v_cvt_pk_bf16_f32 v53, v64, v65
	s_mov_b64 s[0:1], -1
	s_and_b64 vcc, exec, s[36:37]
	global_store_dwordx4 v[116:117], v[50:53], off offset:256
	s_cbranch_vccz .LBB0_247
	s_nop 0
	v_lshl_add_u64 v[50:51], v[114:115], 2, s[24:25]
	global_load_dword v50, v[50:51], off
	s_waitcnt vmcnt(0)
	s_mov_b64 s[0:1], 0
.LBB0_247:
	s_andn2_b64 vcc, exec, s[0:1]
	s_cbranch_vccnz .LBB0_249
	v_mov_b32_e32 v50, v230
.LBB0_249:
	s_waitcnt lgkmcnt(0)
	v_pk_mul_f32 v[46:47], v[46:47], v[50:51] op_sel_hi:[1,0]
	v_pk_mul_f32 v[42:43], v[42:43], v[50:51] op_sel_hi:[1,0]
	v_pk_mul_f32 v[48:49], v[48:49], v[50:51] op_sel_hi:[1,0]
	v_pk_mul_f32 v[44:45], v[44:45], v[50:51] op_sel_hi:[1,0]
	s_and_b64 vcc, exec, s[8:9]
	s_mov_b64 s[0:1], -1
	s_cbranch_vccnz .LBB0_256
	s_and_b64 vcc, exec, s[6:7]
	s_cbranch_vccnz .LBB0_253
	s_andn2_b64 vcc, exec, s[82:83]
	s_cbranch_vccnz .LBB0_338
	v_pk_mul_f32 v[50:51], v[46:47], s[100:101] op_sel_hi:[1,0]
	v_pk_mul_f32 v[52:53], v[48:49], s[100:101] op_sel_hi:[1,0]
	v_pk_mul_f32 v[54:55], v[42:43], s[100:101] op_sel_hi:[1,0]
	v_pk_mul_f32 v[56:57], v[44:45], s[100:101] op_sel_hi:[1,0]
	v_exp_f32_e32 v50, v50
	v_exp_f32_e32 v51, v51
	v_exp_f32_e32 v52, v52
	v_exp_f32_e32 v53, v53
	v_exp_f32_e32 v54, v54
	v_exp_f32_e32 v55, v55
	v_exp_f32_e32 v56, v56
	v_exp_f32_e32 v57, v57
	v_pk_add_f32 v[50:51], v[50:51], s[98:99] op_sel_hi:[1,0]
	v_pk_add_f32 v[52:53], v[52:53], s[98:99] op_sel_hi:[1,0]
	v_pk_add_f32 v[54:55], v[54:55], s[98:99] op_sel_hi:[1,0]
	v_pk_add_f32 v[56:57], v[56:57], s[98:99] op_sel_hi:[1,0]
	v_rcp_f32_e32 v50, v50
	v_rcp_f32_e32 v51, v51
	v_rcp_f32_e32 v52, v52
	v_rcp_f32_e32 v53, v53
	v_rcp_f32_e32 v54, v54
	v_rcp_f32_e32 v55, v55
	v_rcp_f32_e32 v56, v56
	v_rcp_f32_e32 v57, v57
	s_nop 0
	v_pk_mul_f32 v[50:51], v[46:47], v[50:51]
	v_pk_mul_f32 v[52:53], v[48:49], v[52:53]
	v_pk_mul_f32 v[54:55], v[42:43], v[54:55]
	v_pk_mul_f32 v[56:57], v[44:45], v[56:57]
	s_mov_b64 s[0:1], 0

; __device__ __forceinline__ unsigned cvt_pk_bf16(float lo, float hi) { f32x2 v = {lo, hi}; return __builtin_bit_cast(unsigned, __builtin_convertvector(v, nbf16x2e)); }
;     __device__ __forceinline__ void operator()(const f32x4 (&acc)[2][2][4][2], const Unit& u, int wr, int wc, int fr, int fq) const {
;     ...
;                     const int row = row0 + ai * HALF + m * 16; const float rs = rsc ? rsc[row - rbase] : rstd[row];
;                     float v[8];
; #pragma unroll
;                     for (int i = 0; i < 4; ++i) { v[i] = acc[ai][bj][m][0][i] * rs; v[4 + i] = acc[ai][bj][m][1][i] * rs; }
;                     if (seg == 0) {
; #pragma unroll
;                         for (int i = 0; i < 8; ++i) v[i] = v[i] * __builtin_amdgcn_rcpf(1.0f + __expf(-v[i])) * 0.08838834764831845f;
;                     } else if (seg == 1) {
; #pragma unroll
;                         for (int i = 0; i < 8; ++i) { const float s = __builtin_amdgcn_rcpf(1.0f + __expf(-v[i])); v[i] = __logf(lb[i] + (1.0f - lb[i]) * s); }
;                     } else if (seg == 3) {
; #pragma unroll
;                         for (int i = 0; i < 8; ++i) v[i] = v[i] * __builtin_amdgcn_rcpf(1.0f + __expf(-v[i]));
;                     }
;                     u32x4 w; w.x = cvt_pk_bf16(v[0], v[1]); w.y = cvt_pk_bf16(v[2], v[3]); w.z = cvt_pk_bf16(v[4], v[5]); w.w = cvt_pk_bf16(v[6], v[7]);
;                     *(u32x4*)(O + (size_t)row * 2816 + col0) = w;
.LBB0_258:
	s_nop 0
	v_cvt_pk_bf16_f32 v42, v50, v51
	v_cvt_pk_bf16_f32 v43, v52, v53
	v_cvt_pk_bf16_f32 v44, v54, v55
	v_cvt_pk_bf16_f32 v45, v56, v57
	s_mov_b64 s[0:1], -1
	s_and_b64 vcc, exec, s[36:37]
	global_store_dwordx4 v[108:109], v[42:45], off offset:256
	s_cbranch_vccz .LBB0_260
	s_nop 0
	v_lshl_add_u64 v[42:43], v[106:107], 2, s[24:25]
	global_load_dword v42, v[42:43], off
	s_waitcnt vmcnt(0)
	s_mov_b64 s[0:1], 0
.LBB0_260:
	s_andn2_b64 vcc, exec, s[0:1]
	s_cbranch_vccnz .LBB0_262
	v_mov_b32_e32 v42, v231
.LBB0_262:
	s_waitcnt lgkmcnt(0)
	v_pk_mul_f32 v[38:39], v[38:39], v[42:43] op_sel_hi:[1,0]
	v_pk_mul_f32 v[34:35], v[34:35], v[42:43] op_sel_hi:[1,0]
	v_pk_mul_f32 v[40:41], v[40:41], v[42:43] op_sel_hi:[1,0]
	v_pk_mul_f32 v[36:37], v[36:37], v[42:43] op_sel_hi:[1,0]
	s_and_b64 vcc, exec, s[8:9]
	s_mov_b64 s[0:1], -1
	s_cbranch_vccnz .LBB0_269
	s_and_b64 vcc, exec, s[6:7]
	s_cbranch_vccnz .LBB0_266
	s_andn2_b64 vcc, exec, s[82:83]
	s_cbranch_vccnz .LBB0_339
	v_pk_mul_f32 v[42:43], v[38:39], s[100:101] op_sel_hi:[1,0]
	v_pk_mul_f32 v[44:45], v[40:41], s[100:101] op_sel_hi:[1,0]
	v_pk_mul_f32 v[46:47], v[34:35], s[100:101] op_sel_hi:[1,0]
	v_pk_mul_f32 v[48:49], v[36:37], s[100:101] op_sel_hi:[1,0]
	v_exp_f32_e32 v42, v42
	v_exp_f32_e32 v43, v43
	v_exp_f32_e32 v44, v44
	v_exp_f32_e32 v45, v45
	v_exp_f32_e32 v46, v46
	v_exp_f32_e32 v47, v47
	v_exp_f32_e32 v48, v48
	v_exp_f32_e32 v49, v49
	v_pk_add_f32 v[42:43], v[42:43], s[98:99] op_sel_hi:[1,0]
	v_pk_add_f32 v[44:45], v[44:45], s[98:99] op_sel_hi:[1,0]
	v_pk_add_f32 v[46:47], v[46:47], s[98:99] op_sel_hi:[1,0]
	v_pk_add_f32 v[48:49], v[48:49], s[98:99] op_sel_hi:[1,0]
	v_rcp_f32_e32 v42, v42
	v_rcp_f32_e32 v43, v43
	v_rcp_f32_e32 v44, v44
	v_rcp_f32_e32 v45, v45
	v_rcp_f32_e32 v46, v46
	v_rcp_f32_e32 v47, v47
	v_rcp_f32_e32 v48, v48
	v_rcp_f32_e32 v49, v49
	s_nop 0
	v_pk_mul_f32 v[42:43], v[38:39], v[42:43]
	v_pk_mul_f32 v[44:45], v[40:41], v[44:45]
	v_pk_mul_f32 v[46:47], v[34:35], v[46:47]
	v_pk_mul_f32 v[48:49], v[36:37], v[48:49]
	s_mov_b64 s[0:1], 0

; __device__ __forceinline__ unsigned cvt_pk_bf16(float lo, float hi) { f32x2 v = {lo, hi}; return __builtin_bit_cast(unsigned, __builtin_convertvector(v, nbf16x2e)); }
;     __device__ __forceinline__ void operator()(const f32x4 (&acc)[2][2][4][2], const Unit& u, int wr, int wc, int fr, int fq) const {
;     ...
;                     const int row = row0 + ai * HALF + m * 16; const float rs = rsc ? rsc[row - rbase] : rstd[row];
;                     float v[8];
; #pragma unroll
;                     for (int i = 0; i < 4; ++i) { v[i] = acc[ai][bj][m][0][i] * rs; v[4 + i] = acc[ai][bj][m][1][i] * rs; }
;                     if (seg == 0) {
; #pragma unroll
;                         for (int i = 0; i < 8; ++i) v[i] = v[i] * __builtin_amdgcn_rcpf(1.0f + __expf(-v[i])) * 0.08838834764831845f;
;                     } else if (seg == 1) {
; #pragma unroll
;                         for (int i = 0; i < 8; ++i) { const float s = __builtin_amdgcn_rcpf(1.0f + __expf(-v[i])); v[i] = __logf(lb[i] + (1.0f - lb[i]) * s); }
;                     } else if (seg == 3) {
; #pragma unroll
;                         for (int i = 0; i < 8; ++i) v[i] = v[i] * __builtin_amdgcn_rcpf(1.0f + __expf(-v[i]));
;                     }
;                     u32x4 w; w.x = cvt_pk_bf16(v[0], v[1]); w.y = cvt_pk_bf16(v[2], v[3]); w.z = cvt_pk_bf16(v[4], v[5]); w.w = cvt_pk_bf16(v[6], v[7]);
;                     *(u32x4*)(O + (size_t)row * 2816 + col0) = w;
.LBB0_271:
	s_nop 0
	v_cvt_pk_bf16_f32 v34, v42, v43
	v_cvt_pk_bf16_f32 v35, v44, v45
	v_cvt_pk_bf16_f32 v36, v46, v47
	v_cvt_pk_bf16_f32 v37, v48, v49
	s_mov_b64 s[0:1], -1
	s_and_b64 vcc, exec, s[36:37]
	global_store_dwordx4 v[100:101], v[34:37], off offset:256
	s_cbranch_vccz .LBB0_273
	s_nop 0
	v_lshl_add_u64 v[34:35], v[98:99], 2, s[24:25]
	global_load_dword v34, v[34:35], off
	s_waitcnt vmcnt(0)
	s_mov_b64 s[0:1], 0
.LBB0_273:
	s_andn2_b64 vcc, exec, s[0:1]
	s_cbranch_vccnz .LBB0_275
	v_mov_b32_e32 v34, v232
.LBB0_275:
	s_waitcnt lgkmcnt(0)
	v_pk_mul_f32 v[30:31], v[30:31], v[34:35] op_sel_hi:[1,0]
	v_pk_mul_f32 v[26:27], v[26:27], v[34:35] op_sel_hi:[1,0]
	v_pk_mul_f32 v[32:33], v[32:33], v[34:35] op_sel_hi:[1,0]
	v_pk_mul_f32 v[28:29], v[28:29], v[34:35] op_sel_hi:[1,0]
	s_and_b64 vcc, exec, s[8:9]
	s_mov_b64 s[0:1], -1
	s_cbranch_vccnz .LBB0_282
	s_and_b64 vcc, exec, s[6:7]
	s_cbranch_vccnz .LBB0_279
	s_andn2_b64 vcc, exec, s[82:83]
	s_cbranch_vccnz .LBB0_340
	v_pk_mul_f32 v[34:35], v[30:31], s[100:101] op_sel_hi:[1,0]
	v_pk_mul_f32 v[36:37], v[32:33], s[100:101] op_sel_hi:[1,0]
	v_pk_mul_f32 v[38:39], v[26:27], s[100:101] op_sel_hi:[1,0]
	v_pk_mul_f32 v[40:41], v[28:29], s[100:101] op_sel_hi:[1,0]
	v_exp_f32_e32 v34, v34
	v_exp_f32_e32 v35, v35
	v_exp_f32_e32 v36, v36
	v_exp_f32_e32 v37, v37
	v_exp_f32_e32 v38, v38
	v_exp_f32_e32 v39, v39
	v_exp_f32_e32 v40, v40
	v_exp_f32_e32 v41, v41
	v_pk_add_f32 v[34:35], v[34:35], s[98:99] op_sel_hi:[1,0]
	v_pk_add_f32 v[36:37], v[36:37], s[98:99] op_sel_hi:[1,0]
	v_pk_add_f32 v[38:39], v[38:39], s[98:99] op_sel_hi:[1,0]
	v_pk_add_f32 v[40:41], v[40:41], s[98:99] op_sel_hi:[1,0]
	v_rcp_f32_e32 v34, v34
	v_rcp_f32_e32 v35, v35
	v_rcp_f32_e32 v36, v36
	v_rcp_f32_e32 v37, v37
	v_rcp_f32_e32 v38, v38
	v_rcp_f32_e32 v39, v39
	v_rcp_f32_e32 v40, v40
	v_rcp_f32_e32 v41, v41
	s_nop 0
	v_pk_mul_f32 v[34:35], v[30:31], v[34:35]
	v_pk_mul_f32 v[36:37], v[32:33], v[36:37]
	v_pk_mul_f32 v[38:39], v[26:27], v[38:39]
	v_pk_mul_f32 v[40:41], v[28:29], v[40:41]
	s_mov_b64 s[0:1], 0

; __device__ __forceinline__ unsigned cvt_pk_bf16(float lo, float hi) { f32x2 v = {lo, hi}; return __builtin_bit_cast(unsigned, __builtin_convertvector(v, nbf16x2e)); }
;     __device__ __forceinline__ void operator()(const f32x4 (&acc)[2][2][4][2], const Unit& u, int wr, int wc, int fr, int fq) const {
;     ...
;                     const int row = row0 + ai * HALF + m * 16; const float rs = rsc ? rsc[row - rbase] : rstd[row];
;                     float v[8];
; #pragma unroll
;                     for (int i = 0; i < 4; ++i) { v[i] = acc[ai][bj][m][0][i] * rs; v[4 + i] = acc[ai][bj][m][1][i] * rs; }
;                     if (seg == 0) {
; #pragma unroll
;                         for (int i = 0; i < 8; ++i) v[i] = v[i] * __builtin_amdgcn_rcpf(1.0f + __expf(-v[i])) * 0.08838834764831845f;
;                     } else if (seg == 1) {
; #pragma unroll
;                         for (int i = 0; i < 8; ++i) { const float s = __builtin_amdgcn_rcpf(1.0f + __expf(-v[i])); v[i] = __logf(lb[i] + (1.0f - lb[i]) * s); }
;                     } else if (seg == 3) {
; #pragma unroll
;                         for (int i = 0; i < 8; ++i) v[i] = v[i] * __builtin_amdgcn_rcpf(1.0f + __expf(-v[i]));
;                     }
;                     u32x4 w; w.x = cvt_pk_bf16(v[0], v[1]); w.y = cvt_pk_bf16(v[2], v[3]); w.z = cvt_pk_bf16(v[4], v[5]); w.w = cvt_pk_bf16(v[6], v[7]);
;                     *(u32x4*)(O + (size_t)row * 2816 + col0) = w;
.LBB0_284:
	s_nop 0
	v_cvt_pk_bf16_f32 v26, v34, v35
	v_cvt_pk_bf16_f32 v27, v36, v37
	v_cvt_pk_bf16_f32 v28, v38, v39
	v_cvt_pk_bf16_f32 v29, v40, v41
	s_mov_b64 s[0:1], -1
	s_and_b64 vcc, exec, s[36:37]
	global_store_dwordx4 v[92:93], v[26:29], off offset:256
	s_cbranch_vccz .LBB0_286
	s_nop 0
	v_lshl_add_u64 v[26:27], v[90:91], 2, s[24:25]
	global_load_dword v26, v[26:27], off
	s_waitcnt vmcnt(0)
	s_mov_b64 s[0:1], 0
.LBB0_286:
	s_andn2_b64 vcc, exec, s[0:1]
	s_cbranch_vccnz .LBB0_288
	v_mov_b32_e32 v26, v233
.LBB0_288:
	s_waitcnt lgkmcnt(0)
	v_pk_mul_f32 v[22:23], v[22:23], v[26:27] op_sel_hi:[1,0]
	v_pk_mul_f32 v[18:19], v[18:19], v[26:27] op_sel_hi:[1,0]
	v_pk_mul_f32 v[24:25], v[24:25], v[26:27] op_sel_hi:[1,0]
	v_pk_mul_f32 v[20:21], v[20:21], v[26:27] op_sel_hi:[1,0]
	s_and_b64 vcc, exec, s[8:9]
	s_mov_b64 s[0:1], -1
	s_cbranch_vccnz .LBB0_295
	s_and_b64 vcc, exec, s[6:7]
	s_cbranch_vccnz .LBB0_292
	s_andn2_b64 vcc, exec, s[82:83]
	s_cbranch_vccnz .LBB0_341
	v_pk_mul_f32 v[26:27], v[22:23], s[100:101] op_sel_hi:[1,0]
	v_pk_mul_f32 v[28:29], v[24:25], s[100:101] op_sel_hi:[1,0]
	v_pk_mul_f32 v[30:31], v[18:19], s[100:101] op_sel_hi:[1,0]
	v_pk_mul_f32 v[32:33], v[20:21], s[100:101] op_sel_hi:[1,0]
	v_exp_f32_e32 v26, v26
	v_exp_f32_e32 v27, v27
	v_exp_f32_e32 v28, v28
	v_exp_f32_e32 v29, v29
	v_exp_f32_e32 v30, v30
	v_exp_f32_e32 v31, v31
	v_exp_f32_e32 v32, v32
	v_exp_f32_e32 v33, v33
	v_pk_add_f32 v[26:27], v[26:27], s[98:99] op_sel_hi:[1,0]
	v_pk_add_f32 v[28:29], v[28:29], s[98:99] op_sel_hi:[1,0]
	v_pk_add_f32 v[30:31], v[30:31], s[98:99] op_sel_hi:[1,0]
	v_pk_add_f32 v[32:33], v[32:33], s[98:99] op_sel_hi:[1,0]
	v_rcp_f32_e32 v26, v26
	v_rcp_f32_e32 v27, v27
	v_rcp_f32_e32 v28, v28
	v_rcp_f32_e32 v29, v29
	v_rcp_f32_e32 v30, v30
	v_rcp_f32_e32 v31, v31
	v_rcp_f32_e32 v32, v32
	v_rcp_f32_e32 v33, v33
	s_nop 0
	v_pk_mul_f32 v[26:27], v[22:23], v[26:27]
	v_pk_mul_f32 v[28:29], v[24:25], v[28:29]
	v_pk_mul_f32 v[30:31], v[18:19], v[30:31]
	v_pk_mul_f32 v[32:33], v[20:21], v[32:33]
	s_mov_b64 s[0:1], 0

; __device__ __forceinline__ unsigned cvt_pk_bf16(float lo, float hi) { f32x2 v = {lo, hi}; return __builtin_bit_cast(unsigned, __builtin_convertvector(v, nbf16x2e)); }
;     __device__ __forceinline__ void operator()(const f32x4 (&acc)[2][2][4][2], const Unit& u, int wr, int wc, int fr, int fq) const {
;     ...
;                     const int row = row0 + ai * HALF + m * 16; const float rs = rsc ? rsc[row - rbase] : rstd[row];
;                     float v[8];
; #pragma unroll
;                     for (int i = 0; i < 4; ++i) { v[i] = acc[ai][bj][m][0][i] * rs; v[4 + i] = acc[ai][bj][m][1][i] * rs; }
;                     if (seg == 0) {
; #pragma unroll
;                         for (int i = 0; i < 8; ++i) v[i] = v[i] * __builtin_amdgcn_rcpf(1.0f + __expf(-v[i])) * 0.08838834764831845f;
;                     } else if (seg == 1) {
; #pragma unroll
;                         for (int i = 0; i < 8; ++i) { const float s = __builtin_amdgcn_rcpf(1.0f + __expf(-v[i])); v[i] = __logf(lb[i] + (1.0f - lb[i]) * s); }
;                     } else if (seg == 3) {
; #pragma unroll
;                         for (int i = 0; i < 8; ++i) v[i] = v[i] * __builtin_amdgcn_rcpf(1.0f + __expf(-v[i]));
;                     }
;                     u32x4 w; w.x = cvt_pk_bf16(v[0], v[1]); w.y = cvt_pk_bf16(v[2], v[3]); w.z = cvt_pk_bf16(v[4], v[5]); w.w = cvt_pk_bf16(v[6], v[7]);
;                     *(u32x4*)(O + (size_t)row * 2816 + col0) = w;
.LBB0_297:
	s_nop 0
	v_cvt_pk_bf16_f32 v18, v26, v27
	v_cvt_pk_bf16_f32 v19, v28, v29
	v_cvt_pk_bf16_f32 v20, v30, v31
	v_cvt_pk_bf16_f32 v21, v32, v33
	s_mov_b64 s[0:1], -1
	s_and_b64 vcc, exec, s[36:37]
	global_store_dwordx4 v[84:85], v[18:21], off offset:256
	s_cbranch_vccz .LBB0_299
	s_nop 0
	v_lshl_add_u64 v[18:19], v[82:83], 2, s[24:25]
	global_load_dword v18, v[18:19], off
	s_waitcnt vmcnt(0)
	s_mov_b64 s[0:1], 0
.LBB0_299:
	s_andn2_b64 vcc, exec, s[0:1]
	s_cbranch_vccnz .LBB0_301
	v_mov_b32_e32 v18, v234
.LBB0_301:
	s_waitcnt lgkmcnt(0)
	v_pk_mul_f32 v[14:15], v[14:15], v[18:19] op_sel_hi:[1,0]
	v_pk_mul_f32 v[10:11], v[10:11], v[18:19] op_sel_hi:[1,0]
	v_pk_mul_f32 v[16:17], v[16:17], v[18:19] op_sel_hi:[1,0]
	v_pk_mul_f32 v[12:13], v[12:13], v[18:19] op_sel_hi:[1,0]
	s_and_b64 vcc, exec, s[8:9]
	s_mov_b64 s[0:1], -1
	s_cbranch_vccnz .LBB0_308
	s_and_b64 vcc, exec, s[6:7]
	s_cbranch_vccnz .LBB0_305
	s_andn2_b64 vcc, exec, s[82:83]
	s_cbranch_vccnz .LBB0_342
	v_pk_mul_f32 v[18:19], v[14:15], s[100:101] op_sel_hi:[1,0]
	v_pk_mul_f32 v[20:21], v[16:17], s[100:101] op_sel_hi:[1,0]
	v_pk_mul_f32 v[22:23], v[10:11], s[100:101] op_sel_hi:[1,0]
	v_pk_mul_f32 v[24:25], v[12:13], s[100:101] op_sel_hi:[1,0]
	v_exp_f32_e32 v18, v18
	v_exp_f32_e32 v19, v19
	v_exp_f32_e32 v20, v20
	v_exp_f32_e32 v21, v21
	v_exp_f32_e32 v22, v22
	v_exp_f32_e32 v23, v23
	v_exp_f32_e32 v24, v24
	v_exp_f32_e32 v25, v25
	v_pk_add_f32 v[18:19], v[18:19], s[98:99] op_sel_hi:[1,0]
	v_pk_add_f32 v[20:21], v[20:21], s[98:99] op_sel_hi:[1,0]
	v_pk_add_f32 v[22:23], v[22:23], s[98:99] op_sel_hi:[1,0]
	v_pk_add_f32 v[24:25], v[24:25], s[98:99] op_sel_hi:[1,0]
	v_rcp_f32_e32 v18, v18
	v_rcp_f32_e32 v19, v19
	v_rcp_f32_e32 v20, v20
	v_rcp_f32_e32 v21, v21
	v_rcp_f32_e32 v22, v22
	v_rcp_f32_e32 v23, v23
	v_rcp_f32_e32 v24, v24
	v_rcp_f32_e32 v25, v25
	s_nop 0
	v_pk_mul_f32 v[18:19], v[14:15], v[18:19]
	v_pk_mul_f32 v[20:21], v[16:17], v[20:21]
	v_pk_mul_f32 v[22:23], v[10:11], v[22:23]
	v_pk_mul_f32 v[24:25], v[12:13], v[24:25]
	s_mov_b64 s[0:1], 0

; __device__ __forceinline__ unsigned cvt_pk_bf16(float lo, float hi) { f32x2 v = {lo, hi}; return __builtin_bit_cast(unsigned, __builtin_convertvector(v, nbf16x2e)); }
;     __device__ __forceinline__ void operator()(const f32x4 (&acc)[2][2][4][2], const Unit& u, int wr, int wc, int fr, int fq) const {
;     ...
;                     const int row = row0 + ai * HALF + m * 16; const float rs = rsc ? rsc[row - rbase] : rstd[row];
;                     float v[8];
; #pragma unroll
;                     for (int i = 0; i < 4; ++i) { v[i] = acc[ai][bj][m][0][i] * rs; v[4 + i] = acc[ai][bj][m][1][i] * rs; }
;                     if (seg == 0) {
; #pragma unroll
;                         for (int i = 0; i < 8; ++i) v[i] = v[i] * __builtin_amdgcn_rcpf(1.0f + __expf(-v[i])) * 0.08838834764831845f;
;                     } else if (seg == 1) {
; #pragma unroll
;                         for (int i = 0; i < 8; ++i) { const float s = __builtin_amdgcn_rcpf(1.0f + __expf(-v[i])); v[i] = __logf(lb[i] + (1.0f - lb[i]) * s); }
;                     } else if (seg == 3) {
; #pragma unroll
;                         for (int i = 0; i < 8; ++i) v[i] = v[i] * __builtin_amdgcn_rcpf(1.0f + __expf(-v[i]));
;                     }
;                     u32x4 w; w.x = cvt_pk_bf16(v[0], v[1]); w.y = cvt_pk_bf16(v[2], v[3]); w.z = cvt_pk_bf16(v[4], v[5]); w.w = cvt_pk_bf16(v[6], v[7]);
;                     *(u32x4*)(O + (size_t)row * 2816 + col0) = w;
.LBB0_310:
	s_nop 0
	v_cvt_pk_bf16_f32 v10, v18, v19
	v_cvt_pk_bf16_f32 v11, v20, v21
	v_cvt_pk_bf16_f32 v12, v22, v23
	v_cvt_pk_bf16_f32 v13, v24, v25
	s_mov_b64 s[0:1], -1
	s_and_b64 vcc, exec, s[36:37]
	global_store_dwordx4 v[76:77], v[10:13], off offset:256
	s_cbranch_vccz .LBB0_312
	s_nop 0
	v_lshl_add_u64 v[10:11], v[74:75], 2, s[24:25]
	global_load_dword v10, v[10:11], off
	s_waitcnt vmcnt(0)
	s_mov_b64 s[0:1], 0
.LBB0_312:
	s_andn2_b64 vcc, exec, s[0:1]
	s_cbranch_vccnz .LBB0_314
	v_mov_b32_e32 v10, v235
.LBB0_314:
	s_waitcnt lgkmcnt(0)
	v_pk_mul_f32 v[6:7], v[6:7], v[10:11] op_sel_hi:[1,0]
	v_pk_mul_f32 v[2:3], v[2:3], v[10:11] op_sel_hi:[1,0]
	v_pk_mul_f32 v[8:9], v[8:9], v[10:11] op_sel_hi:[1,0]
	v_pk_mul_f32 v[4:5], v[4:5], v[10:11] op_sel_hi:[1,0]
	s_and_b64 vcc, exec, s[8:9]
	s_mov_b64 s[0:1], -1
	s_cbranch_vccnz .LBB0_321
	s_and_b64 vcc, exec, s[6:7]
	s_cbranch_vccnz .LBB0_318
	s_andn2_b64 vcc, exec, s[82:83]
	s_cbranch_vccnz .LBB0_343
	v_pk_mul_f32 v[10:11], v[6:7], s[100:101] op_sel_hi:[1,0]
	v_pk_mul_f32 v[12:13], v[8:9], s[100:101] op_sel_hi:[1,0]
	v_pk_mul_f32 v[14:15], v[2:3], s[100:101] op_sel_hi:[1,0]
	v_pk_mul_f32 v[16:17], v[4:5], s[100:101] op_sel_hi:[1,0]
	v_exp_f32_e32 v10, v10
	v_exp_f32_e32 v11, v11
	v_exp_f32_e32 v12, v12
	v_exp_f32_e32 v13, v13
	v_exp_f32_e32 v14, v14
	v_exp_f32_e32 v15, v15
	v_exp_f32_e32 v16, v16
	v_exp_f32_e32 v17, v17
	v_pk_add_f32 v[10:11], v[10:11], s[98:99] op_sel_hi:[1,0]
	v_pk_add_f32 v[12:13], v[12:13], s[98:99] op_sel_hi:[1,0]
	v_pk_add_f32 v[14:15], v[14:15], s[98:99] op_sel_hi:[1,0]
	v_pk_add_f32 v[16:17], v[16:17], s[98:99] op_sel_hi:[1,0]
	v_rcp_f32_e32 v10, v10
	v_rcp_f32_e32 v11, v11
	v_rcp_f32_e32 v12, v12
	v_rcp_f32_e32 v13, v13
	v_rcp_f32_e32 v14, v14
	v_rcp_f32_e32 v15, v15
	v_rcp_f32_e32 v16, v16
	v_rcp_f32_e32 v17, v17
	s_nop 0
	v_pk_mul_f32 v[10:11], v[6:7], v[10:11]
	v_pk_mul_f32 v[12:13], v[8:9], v[12:13]
	v_pk_mul_f32 v[14:15], v[2:3], v[14:15]
	v_pk_mul_f32 v[16:17], v[4:5], v[16:17]
	s_mov_b64 s[0:1], 0

;     __device__ __forceinline__ void operator()(const f32x4 (&acc)[2][2][4][2], const Unit& u, int wr, int wc, int fr, int fq) const {
;     ...
;                     const int row = row0 + ai * HALF + m * 16; const float rs = rsc ? rsc[row - rbase] : rstd[row];
.LBB0_327:
	v_lshl_add_u64 v[68:69], v[148:149], 2, s[24:25]
	global_load_dword v68, v[68:69], off
	s_waitcnt vmcnt(0)
	s_cbranch_execz .LBB0_222
	s_branch .LBB0_223

; #define PG8_STAGE(bufoff, gbase, voff) do { _Pragma("unroll") for (int _i = 0; _i < 2; ++_i) \
;         __builtin_amdgcn_global_load_lds((const unsigned*)((const char*)(gbase) + (voff)[_i]), (PG8_LAS unsigned*)(lds + (bufoff) + ldsw + _i * 8192), 16, 0, 0); } while (0)
; #define PG8_LDA(dst, b, h) do { _Pragma("unroll") for (int m = 0; m < 4; ++m) _Pragma("unroll") for (int k = 0; k < 2; ++k) dst[m][k] = *(const PG8_LAS bf16x8*)(lds + PG8_SA(b, h) + aoff + m * 2048 + k * 1024); } while (0)
; #define PG8_LDB(dst, b, h) do { _Pragma("unroll") for (int n = 0; n < 2; ++n) _Pragma("unroll") for (int k = 0; k < 2; ++k) dst[n][k] = *(const PG8_LAS bf16x8*)(lds + PG8_SB(b, h) + boff + n * 2048 + k * 1024); } while (0)
; #define PG8_WAIT_V(n) asm volatile("s_waitcnt vmcnt(" #n ")" ::: "memory")
; #define PG8_WAIT_L(n) asm volatile("s_waitcnt lgkmcnt(" #n ")" ::: "memory")
; #define PG8_BAR __builtin_amdgcn_s_barrier()
; #define PG8_SCHED __builtin_amdgcn_sched_barrier(0)
; template <class Epi, class Sched, bool ALIGN_EPI = false, bool SP2 = false>
; __device__ __forceinline__ void gemm_phase(PG8_LAS unsigned char* lds, const Gemm g, const Sched& S, const Epi& E) {
;     ...
;         const bool has_next = S.next(ui + 1, nxt);
;         const char* nA = has_next ? (const char*)g.A + (size_t)nxt.pm * tstep : cA; const char* nB = has_next ? (const char*)g.Bt + (size_t)nxt.pn * tstep : cB;
;         for (int t = 0; t < nt; t += 2) {
;             const bool last = (t == nt - 2);
;             const char* a1 = cA + (size_t)(t + 1) * kstep;
;             const char* a2 = last ? nA : cA + (size_t)(t + 2) * kstep; const char* b2 = last ? nB : cB + (size_t)(t + 2) * kstep;
;             const char* a3 = a2 + kstep; const char* b3 = b2 + kstep;
;             if (last && has_next) S.a_ready(nxt);
;             if constexpr (SP2) {
;             PG8_LDB(B0, 0, 0); PG8_LDB(B1, 0, 1); PG8_SCHED; PG8_LDA(At, 0, 0); PG8_STAGE(PG8_SA(1, 1), a1 + hstep, voffA);
;             PG8_WAIT_V(8); PG8_WAIT_L(0); PG8_BAR; PG8_MMA(0, 0, At, B0); PG8_MMA(0, 1, At, B1); PG8_BAR; PG8_SCHED;
;             PG8_LDA(At, 0, 1); PG8_STAGE(PG8_SB(0, 0), b2, voffB); PG8_STAGE(PG8_SB(0, 1), b2 + hstep, voffB); PG8_STAGE(PG8_SA(0, 0), a2, voffA);
;             PG8_WAIT_V(8); PG8_WAIT_L(0); PG8_BAR; PG8_MMA(1, 0, At, B0); PG8_MMA(1, 1, At, B1); PG8_BAR; PG8_SCHED;
.LBB0_739:
	s_ashr_i32 s19, s18, 31
	s_lshl_b64 s[20:21], s[18:19], 19
	s_add_u32 s20, s42, s20
	s_addc_u32 s21, s43, s21
	s_and_b64 s[22:23], s[0:1], exec
	s_cselect_b32 s19, s21, s31
	s_cselect_b32 s25, s20, s30
	s_ashr_i32 s17, s16, 31
	s_lshl_b64 s[22:23], s[16:17], 19
	s_add_u32 s22, s38, s22
	s_addc_u32 s23, s39, s23
	s_and_b64 s[44:45], s[0:1], exec
	s_cselect_b32 s17, s23, s41
	s_cselect_b32 s27, s22, s40
	s_add_u32 s30, s30, 0x40080
	s_addc_u32 s31, s31, 0
	s_add_u32 s33, s40, 0x100
	s_addc_u32 s70, s41, 0
	s_mov_b32 s71, -2
	ds_read_b128 v[156:159], v152
	ds_read_b128 v[160:163], v152 offset:1024
	ds_read_b128 v[164:167], v152 offset:2048
	ds_read_b128 v[168:171], v152 offset:3072
	ds_read_b128 v[172:175], v153
	ds_read_b128 v[176:179], v153 offset:1024
	ds_read_b128 v[180:183], v153 offset:2048
	ds_read_b128 v[184:187], v153 offset:3072
	s_add_u32 s40, s30, 0xfffc0080
	s_addc_u32 s41, s31, -1
	s_cmp_eq_u32 s71, 12
	s_cselect_b32 s45, s19, s41
	s_cselect_b32 s44, s25, s40
	s_cselect_b32 s41, s17, s70
	s_cselect_b32 s40, s27, s33
	v_lshl_add_u64 v[148:149], s[30:31], 0, v[140:141]
	s_add_i32 m0, s48, 0xc000
	ds_read_b128 v[188:191], v154
	ds_read_b128 v[192:195], v154 offset:1024
	ds_read_b128 v[196:199], v154 offset:2048
	ds_read_b128 v[200:203], v154 offset:3072
	ds_read_b128 v[208:211], v154 offset:4096
	ds_read_b128 v[212:215], v154 offset:5120
	ds_read_b128 v[216:219], v154 offset:6144
	ds_read_b128 v[220:223], v154 offset:7168
	global_load_lds_dwordx4 v[148:149], off
	v_lshl_add_u64 v[148:149], s[30:31], 0, v[142:143]
	s_add_i32 m0, s48, 0xe000
	s_nop 0
	global_load_lds_dwordx4 v[148:149], off
	s_waitcnt vmcnt(16)
	s_cmp_gt_u32 s69, 1
	s_cbranch_scc1 .Lpw_740_0
	s_waitcnt vmcnt(8)
.Lpw_740_0:
	s_waitcnt lgkmcnt(0)
	s_barrier
	s_setprio 1
	s_waitcnt lgkmcnt(0)
	v_mfma_f32_16x16x32_bf16 v[126:129], v[156:159], v[188:191], 0
	v_mfma_f32_16x16x32_bf16 v[122:125], v[164:167], v[188:191], 0
	v_mfma_f32_16x16x32_bf16 v[110:113], v[156:159], v[196:199], 0
	v_mfma_f32_16x16x32_bf16 v[106:109], v[164:167], v[196:199], 0
	v_mfma_f32_16x16x32_bf16 v[94:97], v[156:159], v[208:211], 0
	v_mfma_f32_16x16x32_bf16 v[90:93], v[164:167], v[208:211], 0
	v_mfma_f32_16x16x32_bf16 v[78:81], v[156:159], v[216:219], 0
	v_mfma_f32_16x16x32_bf16 v[74:77], v[164:167], v[216:219], 0
	v_mfma_f32_16x16x32_bf16 v[126:129], v[160:163], v[192:195], v[126:129]
	v_mfma_f32_16x16x32_bf16 v[122:125], v[168:171], v[192:195], v[122:125]
	v_mfma_f32_16x16x32_bf16 v[110:113], v[160:163], v[200:203], v[110:113]
	v_mfma_f32_16x16x32_bf16 v[106:109], v[168:171], v[200:203], v[106:109]
	v_mfma_f32_16x16x32_bf16 v[94:97], v[160:163], v[212:215], v[94:97]
	v_mfma_f32_16x16x32_bf16 v[90:93], v[168:171], v[212:215], v[90:93]
	v_mfma_f32_16x16x32_bf16 v[78:81], v[160:163], v[220:223], v[78:81]
	v_mfma_f32_16x16x32_bf16 v[74:77], v[168:171], v[220:223], v[74:77]
	s_setprio 0
	s_setprio 1
	v_mfma_f32_16x16x32_bf16 v[118:121], v[172:175], v[188:191], 0
	v_mfma_f32_16x16x32_bf16 v[114:117], v[180:183], v[188:191], 0
	v_mfma_f32_16x16x32_bf16 v[102:105], v[172:175], v[196:199], 0
	v_mfma_f32_16x16x32_bf16 v[98:101], v[180:183], v[196:199], 0
	v_mfma_f32_16x16x32_bf16 v[86:89], v[172:175], v[208:211], 0
	v_mfma_f32_16x16x32_bf16 v[82:85], v[180:183], v[208:211], 0
	v_mfma_f32_16x16x32_bf16 v[70:73], v[172:175], v[216:219], 0
	v_mfma_f32_16x16x32_bf16 v[66:69], v[180:183], v[216:219], 0
	v_mfma_f32_16x16x32_bf16 v[118:121], v[176:179], v[192:195], v[118:121]
	v_mfma_f32_16x16x32_bf16 v[114:117], v[184:187], v[192:195], v[114:117]
	v_mfma_f32_16x16x32_bf16 v[102:105], v[176:179], v[200:203], v[102:105]
	v_mfma_f32_16x16x32_bf16 v[98:101], v[184:187], v[200:203], v[98:101]
	v_mfma_f32_16x16x32_bf16 v[86:89], v[176:179], v[212:215], v[86:89]
	v_mfma_f32_16x16x32_bf16 v[82:85], v[184:187], v[212:215], v[82:85]
	v_mfma_f32_16x16x32_bf16 v[70:73], v[176:179], v[220:223], v[70:73]
	v_mfma_f32_16x16x32_bf16 v[66:69], v[184:187], v[220:223], v[66:69]
	s_setprio 0
	s_barrier
	s_add_i32 s72, s66, s47
	s_mov_b32 m0, s72
	ds_read_b128 v[188:191], v154 offset:16384
	ds_read_b128 v[192:195], v154 offset:17408
	ds_read_b128 v[196:199], v154 offset:18432
	ds_read_b128 v[200:203], v154 offset:19456
	ds_read_b128 v[208:211], v154 offset:20480
	ds_read_b128 v[212:215], v154 offset:21504
	ds_read_b128 v[216:219], v154 offset:22528
	ds_read_b128 v[220:223], v154 offset:23552
	global_load_lds_dwordx4 v132, s[40:41]
	s_add_i32 m0, s72, 0x2000
	s_add_u32 s72, s40, 0x40000
	v_lshl_add_u64 v[204:205], s[40:41], 0, v[136:137]
	s_addc_u32 s73, s41, 0
	s_add_i32 s74, s67, s47
	global_load_lds_dwordx4 v136, s[40:41]
	s_mov_b32 m0, s74
	v_lshl_add_u64 v[226:227], s[44:45], 0, v[134:135]
	global_load_lds_dwordx4 v132, s[72:73]
	s_add_i32 m0, s74, 0x2000
	s_nop 0
	global_load_lds_dwordx4 v136, s[72:73]
	v_lshl_add_u64 v[224:225], s[44:45], 0, v[130:131]
	s_mov_b32 m0, s48
	s_nop 0
	global_load_lds_dwordx4 v130, s[44:45]
	s_mov_b32 m0, s49
	s_nop 0
	global_load_lds_dwordx4 v134, s[44:45]
	s_waitcnt vmcnt(16)
	s_cmp_gt_u32 s69, 1
	s_cbranch_scc1 .Lpw_740_1
	s_waitcnt vmcnt(8)
; #define PG8_STAGE(bufoff, gbase, voff) do { _Pragma("unroll") for (int _i = 0; _i < 2; ++_i) \
;         __builtin_amdgcn_global_load_lds((const unsigned*)((const char*)(gbase) + (voff)[_i]), (PG8_LAS unsigned*)(lds + (bufoff) + ldsw + _i * 8192), 16, 0, 0); } while (0)
; #define PG8_LDA(dst, b, h) do { _Pragma("unroll") for (int m = 0; m < 4; ++m) _Pragma("unroll") for (int k = 0; k < 2; ++k) dst[m][k] = *(const PG8_LAS bf16x8*)(lds + PG8_SA(b, h) + aoff + m * 2048 + k * 1024); } while (0)
; #define PG8_LDB(dst, b, h) do { _Pragma("unroll") for (int n = 0; n < 2; ++n) _Pragma("unroll") for (int k = 0; k < 2; ++k) dst[n][k] = *(const PG8_LAS bf16x8*)(lds + PG8_SB(b, h) + boff + n * 2048 + k * 1024); } while (0)
; #define PG8_MMA(ai, bj, At, Bt) do { __builtin_amdgcn_s_setprio(1); _Pragma("unroll") for (int m = 0; m < 4; ++m) _Pragma("unroll") for (int n = 0; n < 2; ++n) _Pragma("unroll") for (int k = 0; k < 2; ++k) \
;         acc[ai][bj][m][n] = __builtin_amdgcn_mfma_f32_16x16x32_bf16(Bt[n][k], At[m][k], acc[ai][bj][m][n], 0, 0, 0); __builtin_amdgcn_s_setprio(0); } while (0)
; #define PG8_WAIT_V(n) asm volatile("s_waitcnt vmcnt(" #n ")" ::: "memory")
; #define PG8_WAIT_L(n) asm volatile("s_waitcnt lgkmcnt(" #n ")" ::: "memory")
; #define PG8_BAR __builtin_amdgcn_s_barrier()
; #define PG8_SCHED __builtin_amdgcn_sched_barrier(0)
; template <class Epi, class Sched, bool ALIGN_EPI = false, bool SP2 = false>
; __device__ __forceinline__ void gemm_phase(PG8_LAS unsigned char* lds, const Gemm g, const Sched& S, const Epi& E) {
;     ...
;             PG8_WAIT_V(8); PG8_WAIT_L(0); PG8_BAR; PG8_MMA(0, 0, At, B0); PG8_MMA(0, 1, At, B1); PG8_BAR; PG8_SCHED;
;             PG8_LDA(At, 0, 1); PG8_STAGE(PG8_SB(0, 0), b2, voffB); PG8_STAGE(PG8_SB(0, 1), b2 + hstep, voffB); PG8_STAGE(PG8_SA(0, 0), a2, voffA);
;             PG8_WAIT_V(8); PG8_WAIT_L(0); PG8_BAR; PG8_MMA(1, 0, At, B0); PG8_MMA(1, 1, At, B1); PG8_BAR; PG8_SCHED;
;             PG8_LDB(B0, 1, 0); PG8_LDB(B1, 1, 1); PG8_SCHED; PG8_LDA(At, 1, 0); PG8_STAGE(PG8_SA(0, 1), a2 + hstep, voffA);
;             PG8_WAIT_V(8); PG8_WAIT_L(0); PG8_BAR; PG8_MMA(0, 0, At, B0); PG8_MMA(0, 1, At, B1); PG8_BAR; PG8_SCHED;
.Lpw_740_1:
	s_waitcnt lgkmcnt(0)
	s_barrier
	s_setprio 1
	s_waitcnt lgkmcnt(0)
	v_mfma_f32_16x16x32_bf16 v[62:65], v[156:159], v[188:191], 0
	v_mfma_f32_16x16x32_bf16 v[58:61], v[164:167], v[188:191], 0
	v_mfma_f32_16x16x32_bf16 v[46:49], v[156:159], v[196:199], 0
	v_mfma_f32_16x16x32_bf16 v[42:45], v[164:167], v[196:199], 0
	v_mfma_f32_16x16x32_bf16 v[30:33], v[156:159], v[208:211], 0
	v_mfma_f32_16x16x32_bf16 v[26:29], v[164:167], v[208:211], 0
	v_mfma_f32_16x16x32_bf16 v[14:17], v[156:159], v[216:219], 0
	v_mfma_f32_16x16x32_bf16 v[10:13], v[164:167], v[216:219], 0
	v_mfma_f32_16x16x32_bf16 v[62:65], v[160:163], v[192:195], v[62:65]
	v_mfma_f32_16x16x32_bf16 v[58:61], v[168:171], v[192:195], v[58:61]
	v_mfma_f32_16x16x32_bf16 v[46:49], v[160:163], v[200:203], v[46:49]
	v_mfma_f32_16x16x32_bf16 v[42:45], v[168:171], v[200:203], v[42:45]
	v_mfma_f32_16x16x32_bf16 v[30:33], v[160:163], v[212:215], v[30:33]
	v_mfma_f32_16x16x32_bf16 v[26:29], v[168:171], v[212:215], v[26:29]
	v_mfma_f32_16x16x32_bf16 v[14:17], v[160:163], v[220:223], v[14:17]
	v_mfma_f32_16x16x32_bf16 v[10:13], v[168:171], v[220:223], v[10:13]
	s_setprio 0
	s_setprio 1
	v_mfma_f32_16x16x32_bf16 v[54:57], v[172:175], v[188:191], 0
	v_mfma_f32_16x16x32_bf16 v[50:53], v[180:183], v[188:191], 0
	v_mfma_f32_16x16x32_bf16 v[38:41], v[172:175], v[196:199], 0
	v_mfma_f32_16x16x32_bf16 v[34:37], v[180:183], v[196:199], 0
	v_mfma_f32_16x16x32_bf16 v[22:25], v[172:175], v[208:211], 0
	v_mfma_f32_16x16x32_bf16 v[18:21], v[180:183], v[208:211], 0
	v_mfma_f32_16x16x32_bf16 v[6:9], v[172:175], v[216:219], 0
	v_mfma_f32_16x16x32_bf16 v[2:5], v[180:183], v[216:219], 0
	v_mfma_f32_16x16x32_bf16 v[54:57], v[176:179], v[192:195], v[54:57]
	v_mfma_f32_16x16x32_bf16 v[50:53], v[184:187], v[192:195], v[50:53]
	v_mfma_f32_16x16x32_bf16 v[38:41], v[176:179], v[200:203], v[38:41]
	v_mfma_f32_16x16x32_bf16 v[34:37], v[184:187], v[200:203], v[34:37]
	v_mfma_f32_16x16x32_bf16 v[22:25], v[176:179], v[212:215], v[22:25]
	v_mfma_f32_16x16x32_bf16 v[18:21], v[184:187], v[212:215], v[18:21]
	v_mfma_f32_16x16x32_bf16 v[6:9], v[176:179], v[220:223], v[6:9]
	v_mfma_f32_16x16x32_bf16 v[2:5], v[184:187], v[220:223], v[2:5]
	s_setprio 0
	s_barrier
	s_add_i32 s72, 0, 0x18000
	v_add_u32_e32 v150, s72, v151
	s_add_i32 s73, 0, 0x1c000
	ds_read_b128 v[156:159], v150
	ds_read_b128 v[160:163], v150 offset:1024
	ds_read_b128 v[164:167], v150 offset:2048
	ds_read_b128 v[168:171], v150 offset:3072
	v_add_u32_e32 v150, s73, v151
	ds_read_b128 v[172:175], v150
	ds_read_b128 v[176:179], v150 offset:1024
	ds_read_b128 v[180:183], v150 offset:2048
	ds_read_b128 v[184:187], v150 offset:3072
	s_add_u32 s44, s44, 0x40000
	s_addc_u32 s45, s45, 0
	s_mov_b32 m0, s50
	ds_read_b128 v[188:191], v154 offset:32768
	ds_read_b128 v[192:195], v154 offset:33792
	ds_read_b128 v[196:199], v154 offset:34816
	ds_read_b128 v[200:203], v154 offset:35840
	ds_read_b128 v[208:211], v154 offset:36864
	ds_read_b128 v[212:215], v154 offset:37888
	ds_read_b128 v[216:219], v154 offset:38912
	ds_read_b128 v[220:223], v154 offset:39936
	global_load_lds_dwordx4 v130, s[44:45]
	s_mov_b32 m0, s51
	s_nop 0
	global_load_lds_dwordx4 v134, s[44:45]
	s_waitcnt vmcnt(8)
	s_waitcnt lgkmcnt(0)
	s_barrier
	s_setprio 1
	s_waitcnt lgkmcnt(0)
	v_mfma_f32_16x16x32_bf16 v[126:129], v[156:159], v[188:191], v[126:129]
	v_mfma_f32_16x16x32_bf16 v[122:125], v[164:167], v[188:191], v[122:125]
	v_mfma_f32_16x16x32_bf16 v[110:113], v[156:159], v[196:199], v[110:113]
	v_mfma_f32_16x16x32_bf16 v[106:109], v[164:167], v[196:199], v[106:109]
	v_mfma_f32_16x16x32_bf16 v[94:97], v[156:159], v[208:211], v[94:97]
	v_mfma_f32_16x16x32_bf16 v[90:93], v[164:167], v[208:211], v[90:93]
	v_mfma_f32_16x16x32_bf16 v[78:81], v[156:159], v[216:219], v[78:81]
	v_mfma_f32_16x16x32_bf16 v[74:77], v[164:167], v[216:219], v[74:77]
	v_mfma_f32_16x16x32_bf16 v[126:129], v[160:163], v[192:195], v[126:129]
	v_mfma_f32_16x16x32_bf16 v[122:125], v[168:171], v[192:195], v[122:125]
	v_mfma_f32_16x16x32_bf16 v[110:113], v[160:163], v[200:203], v[110:113]
	v_mfma_f32_16x16x32_bf16 v[106:109], v[168:171], v[200:203], v[106:109]
	v_mfma_f32_16x16x32_bf16 v[94:97], v[160:163], v[212:215], v[94:97]
	v_mfma_f32_16x16x32_bf16 v[90:93], v[168:171], v[212:215], v[90:93]
	v_mfma_f32_16x16x32_bf16 v[78:81], v[160:163], v[220:223], v[78:81]
	v_mfma_f32_16x16x32_bf16 v[74:77], v[168:171], v[220:223], v[74:77]
	s_setprio 0
	s_setprio 1
	v_mfma_f32_16x16x32_bf16 v[118:121], v[172:175], v[188:191], v[118:121]
	v_mfma_f32_16x16x32_bf16 v[114:117], v[180:183], v[188:191], v[114:117]
	v_mfma_f32_16x16x32_bf16 v[102:105], v[172:175], v[196:199], v[102:105]
	v_mfma_f32_16x16x32_bf16 v[98:101], v[180:183], v[196:199], v[98:101]
	v_mfma_f32_16x16x32_bf16 v[86:89], v[172:175], v[208:211], v[86:89]
	v_mfma_f32_16x16x32_bf16 v[82:85], v[180:183], v[208:211], v[82:85]
	v_mfma_f32_16x16x32_bf16 v[70:73], v[172:175], v[216:219], v[70:73]
	v_mfma_f32_16x16x32_bf16 v[66:69], v[180:183], v[216:219], v[66:69]
	v_mfma_f32_16x16x32_bf16 v[118:121], v[176:179], v[192:195], v[118:121]
	v_mfma_f32_16x16x32_bf16 v[114:117], v[184:187], v[192:195], v[114:117]
	v_mfma_f32_16x16x32_bf16 v[102:105], v[176:179], v[200:203], v[102:105]
	v_mfma_f32_16x16x32_bf16 v[98:101], v[184:187], v[200:203], v[98:101]
	v_mfma_f32_16x16x32_bf16 v[86:89], v[176:179], v[212:215], v[86:89]
	v_mfma_f32_16x16x32_bf16 v[82:85], v[184:187], v[212:215], v[82:85]
	v_mfma_f32_16x16x32_bf16 v[70:73], v[176:179], v[220:223], v[70:73]
	v_mfma_f32_16x16x32_bf16 v[66:69], v[184:187], v[220:223], v[66:69]
	s_setprio 0
	s_barrier
; #define PG8_STAGE(bufoff, gbase, voff) do { _Pragma("unroll") for (int _i = 0; _i < 2; ++_i) \
;         __builtin_amdgcn_global_load_lds((const unsigned*)((const char*)(gbase) + (voff)[_i]), (PG8_LAS unsigned*)(lds + (bufoff) + ldsw + _i * 8192), 16, 0, 0); } while (0)
; #define PG8_LDA(dst, b, h) do { _Pragma("unroll") for (int m = 0; m < 4; ++m) _Pragma("unroll") for (int k = 0; k < 2; ++k) dst[m][k] = *(const PG8_LAS bf16x8*)(lds + PG8_SA(b, h) + aoff + m * 2048 + k * 1024); } while (0)
; #define PG8_MMA(ai, bj, At, Bt) do { __builtin_amdgcn_s_setprio(1); _Pragma("unroll") for (int m = 0; m < 4; ++m) _Pragma("unroll") for (int n = 0; n < 2; ++n) _Pragma("unroll") for (int k = 0; k < 2; ++k) \
;         acc[ai][bj][m][n] = __builtin_amdgcn_mfma_f32_16x16x32_bf16(Bt[n][k], At[m][k], acc[ai][bj][m][n], 0, 0, 0); __builtin_amdgcn_s_setprio(0); } while (0)
; #define PG8_WAIT_V(n) asm volatile("s_waitcnt vmcnt(" #n ")" ::: "memory")
; #define PG8_WAIT_L(n) asm volatile("s_waitcnt lgkmcnt(" #n ")" ::: "memory")
; #define PG8_BAR __builtin_amdgcn_s_barrier()
; #define PG8_SCHED __builtin_amdgcn_sched_barrier(0)
; template <class Epi, class Sched, bool ALIGN_EPI = false, bool SP2 = false>
; __device__ __forceinline__ void gemm_phase(PG8_LAS unsigned char* lds, const Gemm g, const Sched& S, const Epi& E) {
;     ...
;         for (int t = 0; t < nt; t += 2) {
;     ...
;             PG8_LDA(At, 1, 1); PG8_STAGE(PG8_SB(1, 0), b3, voffB); PG8_STAGE(PG8_SB(1, 1), b3 + hstep, voffB); PG8_STAGE(PG8_SA(1, 0), a3, voffA);
;             PG8_WAIT_V(8); PG8_WAIT_L(0); PG8_BAR; PG8_MMA(1, 0, At, B0); PG8_MMA(1, 1, At, B1); PG8_BAR; PG8_SCHED;
	s_add_i32 s44, s72, s47
	s_mov_b32 m0, s44
	ds_read_b128 v[188:191], v154 offset:49152
	ds_read_b128 v[192:195], v154 offset:50176
	ds_read_b128 v[196:199], v154 offset:51200
	ds_read_b128 v[200:203], v154 offset:52224
	ds_read_b128 v[208:211], v154 offset:53248
	ds_read_b128 v[212:215], v154 offset:54272
	ds_read_b128 v[216:219], v154 offset:55296
	ds_read_b128 v[220:223], v154 offset:56320
	s_add_u32 s98, s40, s12
	s_addc_u32 s99, s41, s13
	global_load_lds_dwordx4 v132, s[98:99]
	s_add_i32 m0, s44, 0x2000
	s_add_u32 s40, s40, 0x40080
	v_lshl_add_u64 v[148:149], v[204:205], 0, s[12:13]
	s_addc_u32 s41, s41, 0
	s_add_i32 s44, s73, s47
	global_load_lds_dwordx4 v[148:149], off
	s_mov_b32 m0, s44
	s_nop 0
	global_load_lds_dwordx4 v132, s[40:41]
	s_add_i32 m0, s44, 0x2000
	s_nop 0
	global_load_lds_dwordx4 v136, s[40:41]
	v_lshl_add_u64 v[148:149], v[224:225], 0, s[12:13]
	s_mov_b32 m0, s61
	s_nop 0
	global_load_lds_dwordx4 v[148:149], off
	v_lshl_add_u64 v[148:149], v[226:227], 0, s[12:13]
	s_mov_b32 m0, s62
	s_nop 0
	global_load_lds_dwordx4 v[148:149], off
	s_waitcnt vmcnt(8)
	s_waitcnt lgkmcnt(0)
	s_barrier
	s_setprio 1
	s_waitcnt lgkmcnt(0)
	v_mfma_f32_16x16x32_bf16 v[62:65], v[156:159], v[188:191], v[62:65]
	v_mfma_f32_16x16x32_bf16 v[58:61], v[164:167], v[188:191], v[58:61]
	v_mfma_f32_16x16x32_bf16 v[46:49], v[156:159], v[196:199], v[46:49]
	v_mfma_f32_16x16x32_bf16 v[42:45], v[164:167], v[196:199], v[42:45]
	v_mfma_f32_16x16x32_bf16 v[30:33], v[156:159], v[208:211], v[30:33]
	v_mfma_f32_16x16x32_bf16 v[26:29], v[164:167], v[208:211], v[26:29]
	v_mfma_f32_16x16x32_bf16 v[14:17], v[156:159], v[216:219], v[14:17]
	v_mfma_f32_16x16x32_bf16 v[10:13], v[164:167], v[216:219], v[10:13]
	v_mfma_f32_16x16x32_bf16 v[62:65], v[160:163], v[192:195], v[62:65]
	v_mfma_f32_16x16x32_bf16 v[58:61], v[168:171], v[192:195], v[58:61]
	v_mfma_f32_16x16x32_bf16 v[46:49], v[160:163], v[200:203], v[46:49]
	v_mfma_f32_16x16x32_bf16 v[42:45], v[168:171], v[200:203], v[42:45]
	v_mfma_f32_16x16x32_bf16 v[30:33], v[160:163], v[212:215], v[30:33]
	v_mfma_f32_16x16x32_bf16 v[26:29], v[168:171], v[212:215], v[26:29]
	v_mfma_f32_16x16x32_bf16 v[14:17], v[160:163], v[220:223], v[14:17]
	v_mfma_f32_16x16x32_bf16 v[10:13], v[168:171], v[220:223], v[10:13]
	s_setprio 0
	s_setprio 1
	v_mfma_f32_16x16x32_bf16 v[54:57], v[172:175], v[188:191], v[54:57]
	v_mfma_f32_16x16x32_bf16 v[50:53], v[180:183], v[188:191], v[50:53]
	v_mfma_f32_16x16x32_bf16 v[38:41], v[172:175], v[196:199], v[38:41]
	v_mfma_f32_16x16x32_bf16 v[34:37], v[180:183], v[196:199], v[34:37]
	v_mfma_f32_16x16x32_bf16 v[22:25], v[172:175], v[208:211], v[22:25]
	v_mfma_f32_16x16x32_bf16 v[18:21], v[180:183], v[208:211], v[18:21]
	v_mfma_f32_16x16x32_bf16 v[6:9], v[172:175], v[216:219], v[6:9]
	v_mfma_f32_16x16x32_bf16 v[2:5], v[180:183], v[216:219], v[2:5]
	v_mfma_f32_16x16x32_bf16 v[54:57], v[176:179], v[192:195], v[54:57]
	v_mfma_f32_16x16x32_bf16 v[50:53], v[184:187], v[192:195], v[50:53]
	v_mfma_f32_16x16x32_bf16 v[38:41], v[176:179], v[200:203], v[38:41]
	v_mfma_f32_16x16x32_bf16 v[34:37], v[184:187], v[200:203], v[34:37]
	v_mfma_f32_16x16x32_bf16 v[22:25], v[176:179], v[212:215], v[22:25]
	v_mfma_f32_16x16x32_bf16 v[18:21], v[184:187], v[212:215], v[18:21]
	v_mfma_f32_16x16x32_bf16 v[6:9], v[176:179], v[220:223], v[6:9]
	v_mfma_f32_16x16x32_bf16 v[2:5], v[184:187], v[220:223], v[2:5]
	s_setprio 0
	s_add_i32 s71, s71, 2
	s_add_u32 s30, s30, 0x100
	s_addc_u32 s31, s31, 0
	s_add_u32 s33, s33, 0x100
	s_addc_u32 s70, s70, 0
	s_cmp_gt_u32 s71, 13
	s_barrier
